# up-projection tiles whose 256 rows are all valid run an 8-phase loop copy without EXEC masking around the A pieces
# speedup vs baseline: 1.0176x; 1.0010x over previous
; DI int opaque_tid() { int t = threadIdx.x; asm volatile("" : "+v"(t)); return t; }
; template <bool SWAP>
; DI void gemm_mainloop(f32x16 (&acc)[4][2], const u16* __restrict__ A, int lda, int rlo, int rhi,
;                       const u16* __restrict__ B, int ldb, int K, char* lds, const u16* zero_line) {
;   const int tid = opaque_tid(), lane = tid & 63, w = tid >> 6;
;   const int wm = w >> 2, wn = w & 3;
;   const int h = lane >> 5, r = lane & 31;
;   const int lr = tid >> 3, lc = tid & 7;
; #pragma unroll
;   for (int mi = 0; mi < 4; ++mi)
; #pragma unroll
;     for (int ni = 0; ni < 2; ++ni)
; #pragma unroll
;       for (int i = 0; i < 16; ++i) acc[mi][ni][i] = 0.f;
;   const int gch = (lc ^ ((lr >> 1) & 7)) * 8;
;   const u16* ap = A + (ptrdiff_t)lr * lda + gch;
;   const u16* bp = B + (ptrdiff_t)lr * ldb + gch;
; template <int EPI>
; DI void phase_gemm(const Params& p, const GemmArgs& ga, char* lds) {
;     ...
;   for (int it = 0; it * (int)gridDim.x < total; ++it) {
;     const int lt = logical_index(it);
;     if (lt >= total) continue;
;     int mt, nt;
;     tile_mn(lt, Mt, ga.Nt, mt, nt);
;     int bb, tokbase, S, pos0, rlo = 0, rhi = 256;
;     if (EPI == EPI_UP) {
;       bb = 0; tokbase = 0; S = NTOK;
;       pos0 = 254 * mt - 1;
;       rlo = (mt == 0) ? 1 : 0;
;       rhi = NTOK - pos0; if (rhi > 256) rhi = 256;
;     } else {
;       seq_of_token(mt * 256, bb, tokbase, S);
;       pos0 = mt * 256 - tokbase;
;     }
;     const u16* A = ga.A + (ptrdiff_t)(tokbase + pos0) * ga.lda;
;     const u16* B = ga.Bt + (size_t)(nt * 256) * ga.K;
.LBB0_56:
	s_add_i32 s30, s10, s25
	s_cmpk_gt_i32 s30, 0x10ab
	s_cbranch_scc1 .LBB0_55
	s_mul_hi_i32 s10, s30, 0x2e8ba2e9
	s_lshr_b32 s11, s10, 31
	s_ashr_i32 s10, s10, 5
	s_add_i32 s31, s10, s11
	s_lshl_b32 s10, s31, 3
	s_sub_i32 s11, 0xc2, s10
	s_min_u32 s11, s11, 8
	v_cvt_f32_ubyte0_e32 v0, s11
	v_rcp_iflag_f32_e32 v0, v0
	s_sub_i32 s15, 0, s11
	s_mul_i32 s12, s31, 0xffffff50
	s_add_i32 s12, s12, s30
	v_mul_f32_e32 v0, 0x4f7ffffe, v0
	v_cvt_u32_f32_e32 v0, v0
	s_abs_i32 s14, s12
	s_ashr_i32 s13, s12, 31
	s_waitcnt vmcnt(5)
	v_mov_b32_e32 v13, v204
	v_readfirstlane_b32 s16, v0
	s_mul_i32 s15, s15, s16
	s_mul_hi_u32 s15, s16, s15
	s_add_i32 s16, s16, s15
	s_mul_hi_u32 s15, s14, s16
	s_mul_i32 s16, s15, s11
	s_sub_i32 s14, s14, s16
	s_add_i32 s16, s15, 1
	s_sub_i32 s17, s14, s11
	s_cmp_ge_u32 s14, s11
	s_cselect_b32 s15, s16, s15
	s_cselect_b32 s14, s17, s14
	s_add_i32 s16, s15, 1
	s_cmp_ge_u32 s14, s11
	s_cselect_b32 s14, s16, s15
	s_xor_b32 s14, s14, s13
	s_sub_i32 s28, s14, s13
	s_mul_i32 s34, s28, s11
	s_add_i32 s14, s12, s10
	s_sub_i32 s27, s14, s34
	s_mulk_i32 s27, 0xfe
	s_lshl_b32 s10, s28, 8
	s_add_i32 s20, s27, -1
	s_ashr_i32 s11, s10, 31
	s_ashr_i32 s21, s20, 31
	s_lshl_b64 s[22:23], s[10:11], 11
	v_readlane_b32 s10, v253, 17
	v_readlane_b32 s11, v253, 18
	s_add_u32 s10, s10, s22
	s_addc_u32 s11, s11, s23
	s_lshl_b64 s[12:13], s[20:21], 11
	s_add_u32 s12, s90, s12
	v_ashrrev_i32_e32 v2, 3, v13
	s_waitcnt vmcnt(4)
	v_lshrrev_b32_e32 v15, 1, v2
	s_addc_u32 s13, s91, s13
	s_sub_i32 s15, 0xc001, s27
	v_xor_b32_e32 v0, v15, v13
	v_ashrrev_i32_e32 v3, 31, v2
	s_min_i32 s18, s15, 0x100
	v_lshlrev_b64 v[4:5], 11, v[2:3]
	v_lshlrev_b32_e32 v0, 4, v0
	s_cmp_eq_u32 s14, s34
	v_and_b32_e32 v10, 31, v13
	v_lshl_add_u64 v[6:7], s[12:13], 0, v[4:5]
	v_and_b32_e32 v0, 0x70, v0
	v_lshl_add_u64 v[8:9], s[10:11], 0, v[4:5]
	v_lshrrev_b32_e32 v16, 1, v13
	s_cselect_b64 s[14:15], -1, 0
	v_lshl_add_u64 v[6:7], v[6:7], 0, v[0:1]
	v_lshl_add_u64 v[8:9], v[8:9], 0, v[0:1]
	v_and_or_b32 v0, v16, s51, v10
	v_cndmask_b32_e64 v12, 0, 1, s[14:15]
	v_lshlrev_b32_e32 v175, 7, v0
	v_lshlrev_b32_e32 v0, 7, v13
	v_lshlrev_b32_e32 v177, 4, v13
	v_and_b32_e32 v176, 0x6f80, v0
	v_cmp_ge_i32_e64 s[10:11], v2, v12
	v_cmp_gt_i32_e64 s[12:13], s18, v2
	v_and_b32_e32 v0, 0x70, v177
	v_add_u32_e32 v178, 0x8000, v177
	v_lshl_add_u64 v[158:159], s[80:81], 0, v[0:1]
	s_and_b64 s[10:11], s[10:11], s[12:13]
	v_readfirstlane_b32 s12, v177
	v_cndmask_b32_e64 v11, v159, v7, s[10:11]
	v_cndmask_b32_e64 v10, v158, v6, s[10:11]
	s_mov_b32 m0, s12
	v_readfirstlane_b32 s12, v178
	v_add_u32_e32 v0, 64, v2
	s_barrier
	s_mov_b32 m0, s12
	v_cmp_ge_i32_e64 s[12:13], v0, v12
	v_cmp_gt_i32_e64 s[14:15], s18, v0
	s_mov_b64 s[16:17], 0x20000
	v_add_u32_e32 v0, 0x2000, v177
	v_lshl_add_u64 v[10:11], v[6:7], 0, s[16:17]
	s_and_b64 s[12:13], s[12:13], s[14:15]
	v_readfirstlane_b32 s14, v0
	v_add_u32_e32 v179, 0xa000, v177
	v_cndmask_b32_e64 v11, v159, v11, s[12:13]
	v_cndmask_b32_e64 v10, v158, v10, s[12:13]
	s_mov_b32 m0, s14
	v_readfirstlane_b32 s14, v179
	v_add_u32_e32 v3, 0x80, v2
	v_lshl_add_u64 v[10:11], v[8:9], 0, s[16:17]
	s_mov_b32 m0, s14
	v_cmp_ge_i32_e64 s[14:15], v3, v12
	v_cmp_gt_i32_e64 s[16:17], s18, v3
	s_mov_b64 s[38:39], 0x40000
	v_add_u32_e32 v180, 0x4000, v177
	v_lshl_add_u64 v[10:11], v[6:7], 0, s[38:39]
	s_and_b64 s[14:15], s[14:15], s[16:17]
	v_readfirstlane_b32 s16, v180
	v_add_u32_e32 v181, 0xc000, v177
	v_cndmask_b32_e64 v11, v159, v11, s[14:15]
	v_cndmask_b32_e64 v10, v158, v10, s[14:15]
	s_mov_b32 m0, s16
	v_readfirstlane_b32 s16, v181
	v_add_u32_e32 v2, 0xc0, v2
	v_lshl_add_u64 v[10:11], v[8:9], 0, s[38:39]
	s_mov_b32 m0, s16
	v_cmp_ge_i32_e64 s[16:17], v2, v12
	v_cmp_gt_i32_e64 s[18:19], s18, v2
	s_mov_b64 s[38:39], 0x60000
	v_add_u32_e32 v182, 0x6000, v177
	v_lshl_add_u64 v[2:3], v[6:7], 0, s[38:39]
	s_and_b64 s[16:17], s[16:17], s[18:19]
	v_readfirstlane_b32 s18, v182
	v_add_u32_e32 v183, 0xe000, v177
	v_cndmask_b32_e64 v3, v159, v3, s[16:17]
	v_cndmask_b32_e64 v2, v158, v2, s[16:17]
	s_mov_b32 m0, s18
	v_readfirstlane_b32 s18, v183
	v_lshl_add_u64 v[2:3], v[8:9], 0, s[38:39]
	s_mov_b32 m0, s18
	s_sub_i32 s18, s30, s34
	s_mulk_i32 s31, 0xa8
	v_bfe_u32 v14, v13, 5, 1
	s_sub_i32 s18, s18, s31
	v_bfe_u32 v17, v13, 1, 3
	v_bitop3_b32 v2, v16, v14, 7 bitop3:0x6c
	s_mulk_i32 s18, 0xfe
	v_lshlrev_b32_e32 v185, 4, v2
	v_bitop3_b32 v2, v14, v17, 2 bitop3:0x36
	s_add_i32 s18, s18, -2
	v_lshlrev_b32_e32 v186, 4, v2
	v_bitop3_b32 v2, v14, v17, 4 bitop3:0x36
	s_ashr_i32 s19, s18, 31
	v_lshlrev_b32_e32 v187, 4, v2
	v_bitop3_b32 v2, v14, v17, 6 bitop3:0x36
	s_lshl_b64 s[18:19], s[18:19], 11
	v_bitop3_b32 v6, v15, 7, v13 bitop3:0x48
	v_lshlrev_b32_e32 v188, 4, v2
	v_lshl_add_u64 v[2:3], v[4:5], 0, s[18:19]
	v_lshlrev_b32_e32 v6, 4, v6
	v_or_b32_e32 v2, v2, v6
	v_lshl_add_u64 v[160:161], s[70:71], 0, v[2:3]
	v_lshl_add_u64 v[2:3], v[4:5], 0, s[22:23]
	s_waitcnt vmcnt(0)
	v_or_b32_e32 v2, v2, v6
	v_lshl_add_u64 v[162:163], s[70:71], 0, v[2:3]
	v_mov_b32_e32 v130, 0
	v_mov_b32_e32 v2, 0
	s_mov_b32 s29, 1
	s_mov_b64 s[38:39], 0x3858900
	v_add_u32_e32 v189, 0x10000, v177
	v_add_u32_e32 v190, 0x18000, v177
	v_add_u32_e32 v191, 0x12000, v177
	v_add_u32_e32 v192, 0x1a000, v177
	v_add_u32_e32 v193, 0x14000, v177
	v_add_u32_e32 v194, 0x1c000, v177
	v_add_u32_e32 v195, 0x16000, v177
	v_add_u32_e32 v196, 0x1e000, v177
	v_add_u32_e32 v197, 0x10000, v175
	v_or_b32_e32 v198, 0x10000, v176
	s_mov_b64 s[18:19], 0
	v_mov_b32_e32 v3, v2
	v_mov_b32_e32 v4, v2
	v_mov_b32_e32 v5, v2
	v_mov_b32_e32 v6, v2
	v_mov_b32_e32 v7, v2
	v_mov_b32_e32 v8, v2
	v_mov_b32_e32 v9, v2
	v_mov_b32_e32 v10, v2
	v_mov_b32_e32 v11, v2
	v_mov_b32_e32 v12, v2
	v_mov_b32_e32 v13, v2
	v_mov_b32_e32 v14, v2
	v_mov_b32_e32 v15, v2
	v_mov_b32_e32 v16, v2
	v_mov_b32_e32 v17, v2
	s_waitcnt vmcnt(0)
; template <bool SWAP>
; DI void gemm_mainloop(f32x16 (&acc)[4][2], const u16* __restrict__ A, int lda, int rlo, int rhi,
;                       const u16* __restrict__ B, int ldb, int K, char* lds, const u16* zero_line) {
;     ...
; #pragma unroll
;   for (int mi = 0; mi < 4; ++mi)
; #pragma unroll
;     for (int ni = 0; ni < 2; ++ni)
; #pragma unroll
;       for (int i = 0; i < 16; ++i) acc[mi][ni][i] = 0.f;
;   const int gch = (lc ^ ((lr >> 1) & 7)) * 8;
;   const u16* ap = A + (ptrdiff_t)lr * lda + gch;
;   const u16* bp = B + (ptrdiff_t)lr * ldb + gch;
;   const int nk = K >> 6;
;   typedef __attribute__((address_space(3))) unsigned lds_u32;
;   auto glds = [&](int kt, int st) {
;     char* as_ = lds + st * 65536 + tid * 16;
; #pragma unroll
;     for (int i = 0; i < 4; ++i) {
;       const int rr = lr + 64 * i;
;       const u16* srca = (rr >= rlo && rr < rhi) ? (ap + (ptrdiff_t)(64 * i) * lda + kt * 64) : (zero_line + lc * 8);
;       __builtin_amdgcn_global_load_lds((const unsigned*)srca, (lds_u32*)(as_ + i * 8192), 16, 0, 0);
;       __builtin_amdgcn_global_load_lds((const unsigned*)(bp + (ptrdiff_t)(64 * i) * ldb + kt * 64), (lds_u32*)(as_ + 32768 + i * 8192), 16, 0, 0);
;     }
;   };
;   const int sw = (r >> 1) & 7;
;   const int arow_off = (wm * 128 + r) * 128;
;   const int brow_off = 32768 + (wn * 64 + r) * 128;
;   __syncthreads();
;   glds(0, 0);
;   asm volatile("s_waitcnt vmcnt(0)" ::: "memory");
;   __syncthreads();
	v_mov_b32_e32 v18, v2
	v_mov_b32_e32 v19, v2
	v_mov_b32_e32 v20, v2
	v_mov_b32_e32 v21, v2
	v_mov_b32_e32 v22, v2
	v_mov_b32_e32 v23, v2
	v_mov_b32_e32 v24, v2
	v_mov_b32_e32 v25, v2
	v_mov_b32_e32 v26, v2
	v_mov_b32_e32 v27, v2
	v_mov_b32_e32 v28, v2
	v_mov_b32_e32 v29, v2
	v_mov_b32_e32 v30, v2
	v_mov_b32_e32 v31, v2
	v_mov_b32_e32 v32, v2
	v_mov_b32_e32 v33, v2
	v_mov_b32_e32 v34, v2
	v_mov_b32_e32 v35, v2
	v_mov_b32_e32 v36, v2
	v_mov_b32_e32 v37, v2
	v_mov_b32_e32 v38, v2
	v_mov_b32_e32 v39, v2
	v_mov_b32_e32 v40, v2
	v_mov_b32_e32 v41, v2
	v_mov_b32_e32 v42, v2
	v_mov_b32_e32 v43, v2
	v_mov_b32_e32 v44, v2
	v_mov_b32_e32 v45, v2
	v_mov_b32_e32 v46, v2
	v_mov_b32_e32 v47, v2
	v_mov_b32_e32 v48, v2
	v_mov_b32_e32 v49, v2
	v_mov_b32_e32 v50, v2
	v_mov_b32_e32 v51, v2
	v_mov_b32_e32 v52, v2
	v_mov_b32_e32 v53, v2
	v_mov_b32_e32 v54, v2
	v_mov_b32_e32 v55, v2
	v_mov_b32_e32 v56, v2
	v_mov_b32_e32 v57, v2
	v_mov_b32_e32 v58, v2
	v_mov_b32_e32 v59, v2
	v_mov_b32_e32 v60, v2
	v_mov_b32_e32 v61, v2
	v_mov_b32_e32 v62, v2
	v_mov_b32_e32 v63, v2
	v_mov_b32_e32 v64, v2
	v_mov_b32_e32 v65, v2
	v_mov_b32_e32 v66, v2
	v_mov_b32_e32 v67, v2
	v_mov_b32_e32 v68, v2
	v_mov_b32_e32 v69, v2
	v_mov_b32_e32 v70, v2
	v_mov_b32_e32 v71, v2
	v_mov_b32_e32 v72, v2
	v_mov_b32_e32 v73, v2
	v_mov_b32_e32 v74, v2
	v_mov_b32_e32 v75, v2
	v_mov_b32_e32 v76, v2
	v_mov_b32_e32 v77, v2
	v_mov_b32_e32 v78, v2
	v_mov_b32_e32 v79, v2
	v_mov_b32_e32 v80, v2
	v_mov_b32_e32 v81, v2
	v_mov_b32_e32 v82, v2
	v_mov_b32_e32 v83, v2
	v_mov_b32_e32 v84, v2
	v_mov_b32_e32 v85, v2
	v_mov_b32_e32 v86, v2
	v_mov_b32_e32 v87, v2
	v_mov_b32_e32 v88, v2
	v_mov_b32_e32 v89, v2
	v_mov_b32_e32 v90, v2
	v_mov_b32_e32 v91, v2
	v_mov_b32_e32 v92, v2
	v_mov_b32_e32 v93, v2
	v_mov_b32_e32 v94, v2
	v_mov_b32_e32 v95, v2
	v_mov_b32_e32 v96, v2
	v_mov_b32_e32 v97, v2
	v_mov_b32_e32 v98, v2
	v_mov_b32_e32 v99, v2
	v_mov_b32_e32 v100, v2
	v_mov_b32_e32 v101, v2
	v_mov_b32_e32 v102, v2
	v_mov_b32_e32 v103, v2
	v_mov_b32_e32 v104, v2
	v_mov_b32_e32 v105, v2
	v_mov_b32_e32 v106, v2
	v_mov_b32_e32 v107, v2
	v_mov_b32_e32 v108, v2
	v_mov_b32_e32 v109, v2
	v_mov_b32_e32 v110, v2
	v_mov_b32_e32 v111, v2
	v_mov_b32_e32 v112, v2
	v_mov_b32_e32 v113, v2
	v_mov_b32_e32 v114, v2
	v_mov_b32_e32 v115, v2
	v_mov_b32_e32 v116, v2
	v_mov_b32_e32 v117, v2
	v_mov_b32_e32 v118, v2
	v_mov_b32_e32 v119, v2
	v_mov_b32_e32 v120, v2
	v_mov_b32_e32 v121, v2
	v_mov_b32_e32 v122, v2
	v_mov_b32_e32 v123, v2
	v_mov_b32_e32 v124, v2
	v_mov_b32_e32 v125, v2
	v_mov_b32_e32 v126, v2
	v_mov_b32_e32 v127, v2
	v_mov_b32_e32 v128, v2
	v_mov_b32_e32 v129, v2
	v_mov_b32_e32 v131, v130
	v_mov_b32_e32 v132, v130
	v_mov_b32_e32 v133, v130
	v_mov_b32_e32 v134, v130
	v_mov_b32_e32 v135, v130
	v_mov_b32_e32 v136, v130
	v_mov_b32_e32 v137, v130
	v_mov_b32_e32 v138, v130
	v_mov_b32_e32 v139, v130
	v_mov_b32_e32 v140, v130
	v_mov_b32_e32 v141, v130
	v_mov_b32_e32 v142, v130
	v_mov_b32_e32 v143, v130
	v_mov_b32_e32 v144, v130
	v_mov_b32_e32 v145, v130
	v_mov_b32_e32 v146, v130
	v_mov_b32_e32 v147, v130
	v_mov_b32_e32 v148, v130
	v_mov_b32_e32 v149, v130
	v_mov_b32_e32 v150, v130
	v_mov_b32_e32 v151, v130
	v_mov_b32_e32 v152, v130
	v_mov_b32_e32 v153, v130
	s_mov_b64 s[30:31], 0x37f8900
	s_waitcnt vmcnt(0) lgkmcnt(0)
	s_barrier
	s_add_i32 s18, s27, -1
	s_ashr_i32 s19, s18, 31
	s_lshl_b64 s[18:19], s[18:19], 11
	s_add_u32 s18, s90, s18
	s_addc_u32 s19, s91, s19
	v_readlane_b32 s22, v253, 17
	v_readlane_b32 s23, v253, 18
	s_lshl_b32 s21, s28, 19
	s_add_u32 s22, s22, s21
	s_addc_u32 s23, s23, 0
	v_and_b32_e32 v130, 63, v204
	v_lshrrev_b32_e32 v131, 6, v204
	v_lshrrev_b32_e32 v132, 3, v204
	v_lshrrev_b32_e32 v0, 4, v130
	v_lshl_add_u32 v0, v131, 2, v0
	v_xor_b32_e32 v0, v0, v130
	v_and_b32_e32 v0, 7, v0
	v_lshlrev_b32_e32 v133, 4, v0
	v_lshl_add_u32 v236, v132, 11, v133
	v_add_u32_e32 v237, 0x20000, v236
	v_add_u32_e32 v238, 0x40000, v236
	v_add_u32_e32 v239, 0x60000, v236
	v_and_b32_e32 v0, 31, v132
	v_lshrrev_b32_e32 v130, 5, v132
	v_lshl_add_u32 v0, v130, 6, v0
	v_lshl_add_u32 v240, v0, 11, v133
	v_add_u32_e32 v241, 0x10000, v240
	v_add_u32_e32 v242, 0x40000, v240
	v_add_u32_e32 v243, 0x50000, v240
	v_and_b32_e32 v132, 31, v204
	v_lshrrev_b32_e32 v0, 2, v131
	v_lshl_add_u32 v0, v0, 6, v132
	v_lshlrev_b32_e32 v248, 7, v0
	v_and_b32_e32 v0, 3, v131
	v_lshl_add_u32 v0, v0, 5, v132
	v_lshlrev_b32_e32 v249, 7, v0
	v_bfe_u32 v0, v204, 5, 1
	v_bfe_u32 v130, v132, 1, 3
	v_or_b32_e32 v133, 0, v0
	v_xor_b32_e32 v133, v133, v130
	v_lshlrev_b32_e32 v244, 4, v133
	v_or_b32_e32 v133, 2, v0
	v_xor_b32_e32 v133, v133, v130
	v_lshlrev_b32_e32 v245, 4, v133
	v_or_b32_e32 v133, 4, v0
	v_xor_b32_e32 v133, v133, v130
	v_lshlrev_b32_e32 v246, 4, v133
	v_or_b32_e32 v133, 6, v0
	v_xor_b32_e32 v133, v133, v130
	v_lshlrev_b32_e32 v247, 4, v133
	v_lshlrev_b32_e32 v131, 10, v131
	s_nop 0
	v_readfirstlane_b32 s100, v131
	v_mov_b32_e32 v146, 0
	v_mov_b32_e32 v147, 0
	v_mov_b32_e32 v148, 0
	v_mov_b32_e32 v149, 0
	v_lshlrev_b32_e32 v130, 4, v204
	v_add_u32_e32 v132, 0x10000, v130
	s_not_b64 exec, s[10:11]
	ds_write_b128 v130, v[146:149]
	ds_write_b128 v132, v[146:149]
	s_not_b64 exec, s[12:13]
	ds_write_b128 v130, v[146:149] offset:16384
	ds_write_b128 v132, v[146:149] offset:16384
	s_not_b64 exec, s[14:15]
	ds_write_b128 v130, v[146:149] offset:8192
	ds_write_b128 v132, v[146:149] offset:8192
	s_not_b64 exec, s[16:17]
	ds_write_b128 v130, v[146:149] offset:24576
	ds_write_b128 v132, v[146:149] offset:24576
	s_mov_b64 exec, -1
	s_mov_b32 s29, 0
	s_mov_b32 s21, 0x10000
	s_waitcnt lgkmcnt(0)
	s_cmp_eq_u32 s27, 0
	s_cbranch_scc1 .Lg8_u0_msk
	s_cmp_gt_i32 s20, 0xbf00
	s_cbranch_scc1 .Lg8_u0_msk
	s_add_u32 m0, s100, 0x8000
	s_nop 0
	global_load_lds_dwordx4 v240, s[22:23]
	v_add_u32_e32 v240, 0x80, v240
	s_add_u32 m0, s100, 0xa000
	s_nop 0
	global_load_lds_dwordx4 v242, s[22:23]
	v_add_u32_e32 v242, 0x80, v242
	s_add_u32 m0, s100, 0x0
	s_nop 0
	global_load_lds_dwordx4 v236, s[18:19]
	v_add_u32_e32 v236, 0x80, v236
	s_add_u32 m0, s100, 0x2000
	s_nop 0
	global_load_lds_dwordx4 v238, s[18:19]
	v_add_u32_e32 v238, 0x80, v238
	s_add_u32 m0, s100, 0xc000
	s_nop 0
	global_load_lds_dwordx4 v241, s[22:23]
	v_add_u32_e32 v241, 0x80, v241
	s_add_u32 m0, s100, 0xe000
	s_nop 0
	global_load_lds_dwordx4 v243, s[22:23]
	v_add_u32_e32 v243, 0x80, v243
	s_add_u32 m0, s100, 0x4000
	s_nop 0
	global_load_lds_dwordx4 v237, s[18:19]
	v_add_u32_e32 v237, 0x80, v237
	s_add_u32 m0, s100, 0x6000
	s_nop 0
	global_load_lds_dwordx4 v239, s[18:19]
	v_add_u32_e32 v239, 0x80, v239
	s_cmp_eq_u32 s101, 1
	s_cbranch_scc0 .Lg8_u0u_p0
	s_barrier
; template <bool SWAP>
; DI void gemm_mainloop(f32x16 (&acc)[4][2], const u16* __restrict__ A, int lda, int rlo, int rhi,
;                       const u16* __restrict__ B, int ldb, int K, char* lds, const u16* zero_line) {
;     ...
; #pragma unroll 2
;   for (int kt = 0; kt < nk; ++kt) {
;     const char* st = lds + (kt & 1) * 65536;
;     ldfrag(st, 0, 0);
;     mma(1);
;     pat_rd();
;     if (kt + 1 < nk) glds(kt + 1, (kt + 1) & 1);
;     ldfrag(st, 1, 1);
;     mma(0);
;     pat_rd();
;     ldfrag(st, 2, 0);
;     mma(1);
;     pat_rd();
;     ldfrag(st, 3, 1);
;     mma(0);
;     pat_rd();
;     asm volatile("s_waitcnt vmcnt(0)" ::: "memory");
;     __syncthreads();
;   }
.Lg8_u0u_p0:
	s_waitcnt vmcnt(4)
	s_barrier
	s_add_u32 m0, s100, 0x18000
	s_nop 0
	global_load_lds_dwordx4 v240, s[22:23]
	v_add_u32_e32 v240, 0x80, v240
	s_add_u32 m0, s100, 0x1a000
	s_nop 0
	global_load_lds_dwordx4 v242, s[22:23]
	v_add_u32_e32 v242, 0x80, v242
	s_add_u32 m0, s100, 0x10000
	s_nop 0
	global_load_lds_dwordx4 v236, s[18:19]
	v_add_u32_e32 v236, 0x80, v236
	s_add_u32 m0, s100, 0x12000
	s_nop 0
	global_load_lds_dwordx4 v238, s[18:19]
	v_add_u32_e32 v238, 0x80, v238
	s_add_u32 m0, s100, 0x1c000
	s_nop 0
	global_load_lds_dwordx4 v241, s[22:23]
	v_add_u32_e32 v241, 0x80, v241
	s_add_u32 m0, s100, 0x1e000
	s_nop 0
	global_load_lds_dwordx4 v243, s[22:23]
	v_add_u32_e32 v243, 0x80, v243
	s_waitcnt vmcnt(6)
	s_barrier
	v_add3_u32 v166, v249, v244, 0
	v_add3_u32 v167, v249, v245, 0
	v_add3_u32 v175, v249, v246, 0
	v_add3_u32 v185, v249, v247, 0
	ds_read_b128 v[176:179], v166 offset:32768
	ds_read_b128 v[180:183], v167 offset:32768
	ds_read_b128 v[186:189], v175 offset:32768
	ds_read_b128 v[190:193], v185 offset:32768
.Lg8_u0u:
	v_add3_u32 v166, v248, v244, 0
	v_add3_u32 v167, v248, v245, 0
	v_add3_u32 v175, v248, v246, 0
	v_add3_u32 v185, v248, v247, 0
	ds_read_b128 v[130:133], v166
	ds_read_b128 v[134:137], v167
	ds_read_b128 v[138:141], v175
	ds_read_b128 v[142:145], v185
	ds_read_b128 v[146:149], v166 offset:4096
	ds_read_b128 v[150:153], v167 offset:4096
	ds_read_b128 v[158:161], v175 offset:4096
	ds_read_b128 v[162:165], v185 offset:4096
	s_add_u32 m0, s100, 0x14000
	s_nop 0
	global_load_lds_dwordx4 v237, s[18:19]
	v_add_u32_e32 v237, 0x80, v237
	s_add_u32 m0, s100, 0x16000
	s_nop 0
	global_load_lds_dwordx4 v239, s[18:19]
	v_add_u32_e32 v239, 0x80, v239
	s_barrier
	s_waitcnt lgkmcnt(0)
	v_mfma_f32_32x32x16_bf16 v[114:129], v[176:179], v[130:133], v[114:129]
	v_mfma_f32_32x32x16_bf16 v[82:97], v[176:179], v[146:149], v[82:97]
	v_mfma_f32_32x32x16_bf16 v[114:129], v[180:183], v[134:137], v[114:129]
	v_mfma_f32_32x32x16_bf16 v[82:97], v[180:183], v[150:153], v[82:97]
	v_mfma_f32_32x32x16_bf16 v[114:129], v[186:189], v[138:141], v[114:129]
	v_mfma_f32_32x32x16_bf16 v[82:97], v[186:189], v[158:161], v[82:97]
	v_mfma_f32_32x32x16_bf16 v[114:129], v[190:193], v[142:145], v[114:129]
	v_mfma_f32_32x32x16_bf16 v[82:97], v[190:193], v[162:165], v[82:97]
	s_barrier
	v_add3_u32 v166, v249, v244, 0
	v_add3_u32 v167, v249, v245, 0
	v_add3_u32 v175, v249, v246, 0
	v_add3_u32 v185, v249, v247, 0
	ds_read_b128 v[194:197], v166 offset:49152
	ds_read_b128 v[198:201], v167 offset:49152
	ds_read_b128 v[228:231], v175 offset:49152
	ds_read_b128 v[232:235], v185 offset:49152
	s_add_u32 m0, s100, 0x8000
	s_nop 0
	global_load_lds_dwordx4 v240, s[22:23]
	v_add_u32_e32 v240, 0x80, v240
	s_add_u32 m0, s100, 0xa000
	s_nop 0
	global_load_lds_dwordx4 v242, s[22:23]
	v_add_u32_e32 v242, 0x80, v242
	s_barrier
	s_waitcnt lgkmcnt(0)
	v_mfma_f32_32x32x16_bf16 v[98:113], v[194:197], v[130:133], v[98:113]
	v_mfma_f32_32x32x16_bf16 v[66:81], v[194:197], v[146:149], v[66:81]
	v_mfma_f32_32x32x16_bf16 v[98:113], v[198:201], v[134:137], v[98:113]
	v_mfma_f32_32x32x16_bf16 v[66:81], v[198:201], v[150:153], v[66:81]
	v_mfma_f32_32x32x16_bf16 v[98:113], v[228:231], v[138:141], v[98:113]
	v_mfma_f32_32x32x16_bf16 v[66:81], v[228:231], v[158:161], v[66:81]
	v_mfma_f32_32x32x16_bf16 v[98:113], v[232:235], v[142:145], v[98:113]
	v_mfma_f32_32x32x16_bf16 v[66:81], v[232:235], v[162:165], v[66:81]
	s_barrier
	v_add3_u32 v166, v248, v244, 0
	v_add3_u32 v167, v248, v245, 0
	v_add3_u32 v175, v248, v246, 0
	v_add3_u32 v185, v248, v247, 0
	ds_read_b128 v[130:133], v166 offset:16384
	ds_read_b128 v[134:137], v167 offset:16384
	ds_read_b128 v[138:141], v175 offset:16384
	ds_read_b128 v[142:145], v185 offset:16384
	ds_read_b128 v[146:149], v166 offset:20480
	ds_read_b128 v[150:153], v167 offset:20480
	ds_read_b128 v[158:161], v175 offset:20480
	ds_read_b128 v[162:165], v185 offset:20480
	s_add_u32 m0, s100, 0x0
	s_nop 0
	global_load_lds_dwordx4 v236, s[18:19]
	v_add_u32_e32 v236, 0x80, v236
	s_add_u32 m0, s100, 0x2000
	s_nop 0
	global_load_lds_dwordx4 v238, s[18:19]
	v_add_u32_e32 v238, 0x80, v238
	s_waitcnt vmcnt(10)
	s_barrier
	s_waitcnt lgkmcnt(0)
	v_mfma_f32_32x32x16_bf16 v[50:65], v[176:179], v[130:133], v[50:65]
	v_mfma_f32_32x32x16_bf16 v[18:33], v[176:179], v[146:149], v[18:33]
	v_mfma_f32_32x32x16_bf16 v[50:65], v[180:183], v[134:137], v[50:65]
	v_mfma_f32_32x32x16_bf16 v[18:33], v[180:183], v[150:153], v[18:33]
	v_mfma_f32_32x32x16_bf16 v[50:65], v[186:189], v[138:141], v[50:65]
	v_mfma_f32_32x32x16_bf16 v[18:33], v[186:189], v[158:161], v[18:33]
	v_mfma_f32_32x32x16_bf16 v[50:65], v[190:193], v[142:145], v[50:65]
	v_mfma_f32_32x32x16_bf16 v[18:33], v[190:193], v[162:165], v[18:33]
	s_barrier
	v_add3_u32 v166, v249, v244, s21
	v_add3_u32 v167, v249, v245, s21
	v_add3_u32 v175, v249, v246, s21
	v_add3_u32 v185, v249, v247, s21
	ds_read_b128 v[176:179], v166 offset:32768
	ds_read_b128 v[180:183], v167 offset:32768
	ds_read_b128 v[186:189], v175 offset:32768
	ds_read_b128 v[190:193], v185 offset:32768
	s_add_u32 m0, s100, 0xc000
	s_nop 0
	global_load_lds_dwordx4 v241, s[22:23]
	v_add_u32_e32 v241, 0x80, v241
	s_add_u32 m0, s100, 0xe000
	s_nop 0
	global_load_lds_dwordx4 v243, s[22:23]
	v_add_u32_e32 v243, 0x80, v243
	s_waitcnt vmcnt(6)
	s_barrier
	s_waitcnt lgkmcnt(0)
	v_mfma_f32_32x32x16_bf16 v[34:49], v[194:197], v[130:133], v[34:49]
	v_mfma_f32_32x32x16_bf16 v[2:17], v[194:197], v[146:149], v[2:17]
	v_mfma_f32_32x32x16_bf16 v[34:49], v[198:201], v[134:137], v[34:49]
	v_mfma_f32_32x32x16_bf16 v[2:17], v[198:201], v[150:153], v[2:17]
	v_mfma_f32_32x32x16_bf16 v[34:49], v[228:231], v[138:141], v[34:49]
	v_mfma_f32_32x32x16_bf16 v[2:17], v[228:231], v[158:161], v[2:17]
	v_mfma_f32_32x32x16_bf16 v[34:49], v[232:235], v[142:145], v[34:49]
	v_mfma_f32_32x32x16_bf16 v[2:17], v[232:235], v[162:165], v[2:17]
	s_barrier
; template <bool SWAP>
; DI void gemm_mainloop(f32x16 (&acc)[4][2], const u16* __restrict__ A, int lda, int rlo, int rhi,
;                       const u16* __restrict__ B, int ldb, int K, char* lds, const u16* zero_line) {
;     ...
; #pragma unroll 2
;   for (int kt = 0; kt < nk; ++kt) {
;     const char* st = lds + (kt & 1) * 65536;
;     ldfrag(st, 0, 0);
;     mma(1);
;     pat_rd();
;     if (kt + 1 < nk) glds(kt + 1, (kt + 1) & 1);
;     ldfrag(st, 1, 1);
;     mma(0);
;     pat_rd();
;     ldfrag(st, 2, 0);
;     mma(1);
;     pat_rd();
;     ldfrag(st, 3, 1);
;     mma(0);
;     pat_rd();
;     asm volatile("s_waitcnt vmcnt(0)" ::: "memory");
;     __syncthreads();
;   }
	v_add3_u32 v166, v248, v244, s21
	v_add3_u32 v167, v248, v245, s21
	v_add3_u32 v175, v248, v246, s21
	v_add3_u32 v185, v248, v247, s21
	ds_read_b128 v[130:133], v166
	ds_read_b128 v[134:137], v167
	ds_read_b128 v[138:141], v175
	ds_read_b128 v[142:145], v185
	ds_read_b128 v[146:149], v166 offset:4096
	ds_read_b128 v[150:153], v167 offset:4096
	ds_read_b128 v[158:161], v175 offset:4096
	ds_read_b128 v[162:165], v185 offset:4096
	s_add_u32 m0, s100, 0x4000
	s_nop 0
	global_load_lds_dwordx4 v237, s[18:19]
	v_add_u32_e32 v237, 0x80, v237
	s_add_u32 m0, s100, 0x6000
	s_nop 0
	global_load_lds_dwordx4 v239, s[18:19]
	v_add_u32_e32 v239, 0x80, v239
	s_barrier
	s_waitcnt lgkmcnt(0)
	v_mfma_f32_32x32x16_bf16 v[114:129], v[176:179], v[130:133], v[114:129]
	v_mfma_f32_32x32x16_bf16 v[82:97], v[176:179], v[146:149], v[82:97]
	v_mfma_f32_32x32x16_bf16 v[114:129], v[180:183], v[134:137], v[114:129]
	v_mfma_f32_32x32x16_bf16 v[82:97], v[180:183], v[150:153], v[82:97]
	v_mfma_f32_32x32x16_bf16 v[114:129], v[186:189], v[138:141], v[114:129]
	v_mfma_f32_32x32x16_bf16 v[82:97], v[186:189], v[158:161], v[82:97]
	v_mfma_f32_32x32x16_bf16 v[114:129], v[190:193], v[142:145], v[114:129]
	v_mfma_f32_32x32x16_bf16 v[82:97], v[190:193], v[162:165], v[82:97]
	s_barrier
	v_add3_u32 v166, v249, v244, s21
	v_add3_u32 v167, v249, v245, s21
	v_add3_u32 v175, v249, v246, s21
	v_add3_u32 v185, v249, v247, s21
	ds_read_b128 v[194:197], v166 offset:49152
	ds_read_b128 v[198:201], v167 offset:49152
	ds_read_b128 v[228:231], v175 offset:49152
	ds_read_b128 v[232:235], v185 offset:49152
	s_add_u32 m0, s100, 0x18000
	s_nop 0
	global_load_lds_dwordx4 v240, s[22:23]
	v_add_u32_e32 v240, 0x80, v240
	s_add_u32 m0, s100, 0x1a000
	s_nop 0
	global_load_lds_dwordx4 v242, s[22:23]
	v_add_u32_e32 v242, 0x80, v242
	s_barrier
	s_waitcnt lgkmcnt(0)
	v_mfma_f32_32x32x16_bf16 v[98:113], v[194:197], v[130:133], v[98:113]
	v_mfma_f32_32x32x16_bf16 v[66:81], v[194:197], v[146:149], v[66:81]
	v_mfma_f32_32x32x16_bf16 v[98:113], v[198:201], v[134:137], v[98:113]
	v_mfma_f32_32x32x16_bf16 v[66:81], v[198:201], v[150:153], v[66:81]
	v_mfma_f32_32x32x16_bf16 v[98:113], v[228:231], v[138:141], v[98:113]
	v_mfma_f32_32x32x16_bf16 v[66:81], v[228:231], v[158:161], v[66:81]
	v_mfma_f32_32x32x16_bf16 v[98:113], v[232:235], v[142:145], v[98:113]
	v_mfma_f32_32x32x16_bf16 v[66:81], v[232:235], v[162:165], v[66:81]
	s_barrier
	v_add3_u32 v166, v248, v244, s21
	v_add3_u32 v167, v248, v245, s21
	v_add3_u32 v175, v248, v246, s21
	v_add3_u32 v185, v248, v247, s21
	ds_read_b128 v[130:133], v166 offset:16384
	ds_read_b128 v[134:137], v167 offset:16384
	ds_read_b128 v[138:141], v175 offset:16384
	ds_read_b128 v[142:145], v185 offset:16384
	ds_read_b128 v[146:149], v166 offset:20480
	ds_read_b128 v[150:153], v167 offset:20480
	ds_read_b128 v[158:161], v175 offset:20480
	ds_read_b128 v[162:165], v185 offset:20480
	s_add_u32 m0, s100, 0x10000
	s_nop 0
	global_load_lds_dwordx4 v236, s[18:19]
	v_add_u32_e32 v236, 0x80, v236
	s_add_u32 m0, s100, 0x12000
	s_nop 0
	global_load_lds_dwordx4 v238, s[18:19]
	v_add_u32_e32 v238, 0x80, v238
	s_waitcnt vmcnt(10)
	s_barrier
	s_waitcnt lgkmcnt(0)
	v_mfma_f32_32x32x16_bf16 v[50:65], v[176:179], v[130:133], v[50:65]
	v_mfma_f32_32x32x16_bf16 v[18:33], v[176:179], v[146:149], v[18:33]
	v_mfma_f32_32x32x16_bf16 v[50:65], v[180:183], v[134:137], v[50:65]
	v_mfma_f32_32x32x16_bf16 v[18:33], v[180:183], v[150:153], v[18:33]
	v_mfma_f32_32x32x16_bf16 v[50:65], v[186:189], v[138:141], v[50:65]
	v_mfma_f32_32x32x16_bf16 v[18:33], v[186:189], v[158:161], v[18:33]
	v_mfma_f32_32x32x16_bf16 v[50:65], v[190:193], v[142:145], v[50:65]
	v_mfma_f32_32x32x16_bf16 v[18:33], v[190:193], v[162:165], v[18:33]
	s_barrier
	v_add3_u32 v166, v249, v244, 0
	v_add3_u32 v167, v249, v245, 0
	v_add3_u32 v175, v249, v246, 0
	v_add3_u32 v185, v249, v247, 0
	ds_read_b128 v[176:179], v166 offset:32768
	ds_read_b128 v[180:183], v167 offset:32768
	ds_read_b128 v[186:189], v175 offset:32768
	ds_read_b128 v[190:193], v185 offset:32768
	s_add_u32 m0, s100, 0x1c000
	s_nop 0
	global_load_lds_dwordx4 v241, s[22:23]
	v_add_u32_e32 v241, 0x80, v241
	s_add_u32 m0, s100, 0x1e000
	s_nop 0
	global_load_lds_dwordx4 v243, s[22:23]
	v_add_u32_e32 v243, 0x80, v243
	s_waitcnt vmcnt(6)
	s_barrier
	s_waitcnt lgkmcnt(0)
	v_mfma_f32_32x32x16_bf16 v[34:49], v[194:197], v[130:133], v[34:49]
	v_mfma_f32_32x32x16_bf16 v[2:17], v[194:197], v[146:149], v[2:17]
	v_mfma_f32_32x32x16_bf16 v[34:49], v[198:201], v[134:137], v[34:49]
	v_mfma_f32_32x32x16_bf16 v[2:17], v[198:201], v[150:153], v[2:17]
	v_mfma_f32_32x32x16_bf16 v[34:49], v[228:231], v[138:141], v[34:49]
	v_mfma_f32_32x32x16_bf16 v[2:17], v[228:231], v[158:161], v[2:17]
	v_mfma_f32_32x32x16_bf16 v[34:49], v[232:235], v[142:145], v[34:49]
	v_mfma_f32_32x32x16_bf16 v[2:17], v[232:235], v[162:165], v[2:17]
	s_barrier
	s_add_i32 s29, s29, 2
	s_cmp_lt_u32 s29, 14
	s_cbranch_scc1 .Lg8_u0u
	v_add3_u32 v166, v248, v244, 0
	v_add3_u32 v167, v248, v245, 0
	v_add3_u32 v175, v248, v246, 0
	v_add3_u32 v185, v248, v247, 0
	ds_read_b128 v[130:133], v166
	ds_read_b128 v[134:137], v167
	ds_read_b128 v[138:141], v175
	ds_read_b128 v[142:145], v185
	ds_read_b128 v[146:149], v166 offset:4096
	ds_read_b128 v[150:153], v167 offset:4096
	ds_read_b128 v[158:161], v175 offset:4096
	ds_read_b128 v[162:165], v185 offset:4096
	s_add_u32 m0, s100, 0x14000
	s_nop 0
	global_load_lds_dwordx4 v237, s[18:19]
	v_add_u32_e32 v237, 0x80, v237
	s_add_u32 m0, s100, 0x16000
	s_nop 0
	global_load_lds_dwordx4 v239, s[18:19]
	v_add_u32_e32 v239, 0x80, v239
	s_barrier
; template <bool SWAP>
; DI void gemm_mainloop(f32x16 (&acc)[4][2], const u16* __restrict__ A, int lda, int rlo, int rhi,
;                       const u16* __restrict__ B, int ldb, int K, char* lds, const u16* zero_line) {
;     ...
; #pragma unroll 2
;   for (int kt = 0; kt < nk; ++kt) {
;     const char* st = lds + (kt & 1) * 65536;
;     ldfrag(st, 0, 0);
;     mma(1);
;     pat_rd();
;     if (kt + 1 < nk) glds(kt + 1, (kt + 1) & 1);
;     ldfrag(st, 1, 1);
;     mma(0);
;     pat_rd();
;     ldfrag(st, 2, 0);
;     mma(1);
;     pat_rd();
;     ldfrag(st, 3, 1);
;     mma(0);
;     pat_rd();
;     asm volatile("s_waitcnt vmcnt(0)" ::: "memory");
;     __syncthreads();
;   }
	s_waitcnt lgkmcnt(0)
	v_mfma_f32_32x32x16_bf16 v[114:129], v[176:179], v[130:133], v[114:129]
	v_mfma_f32_32x32x16_bf16 v[82:97], v[176:179], v[146:149], v[82:97]
	v_mfma_f32_32x32x16_bf16 v[114:129], v[180:183], v[134:137], v[114:129]
	v_mfma_f32_32x32x16_bf16 v[82:97], v[180:183], v[150:153], v[82:97]
	v_mfma_f32_32x32x16_bf16 v[114:129], v[186:189], v[138:141], v[114:129]
	v_mfma_f32_32x32x16_bf16 v[82:97], v[186:189], v[158:161], v[82:97]
	v_mfma_f32_32x32x16_bf16 v[114:129], v[190:193], v[142:145], v[114:129]
	v_mfma_f32_32x32x16_bf16 v[82:97], v[190:193], v[162:165], v[82:97]
	s_barrier
	v_add3_u32 v166, v249, v244, 0
	v_add3_u32 v167, v249, v245, 0
	v_add3_u32 v175, v249, v246, 0
	v_add3_u32 v185, v249, v247, 0
	ds_read_b128 v[194:197], v166 offset:49152
	ds_read_b128 v[198:201], v167 offset:49152
	ds_read_b128 v[228:231], v175 offset:49152
	ds_read_b128 v[232:235], v185 offset:49152
	s_barrier
	s_waitcnt lgkmcnt(0)
	v_mfma_f32_32x32x16_bf16 v[98:113], v[194:197], v[130:133], v[98:113]
	v_mfma_f32_32x32x16_bf16 v[66:81], v[194:197], v[146:149], v[66:81]
	v_mfma_f32_32x32x16_bf16 v[98:113], v[198:201], v[134:137], v[98:113]
	v_mfma_f32_32x32x16_bf16 v[66:81], v[198:201], v[150:153], v[66:81]
	v_mfma_f32_32x32x16_bf16 v[98:113], v[228:231], v[138:141], v[98:113]
	v_mfma_f32_32x32x16_bf16 v[66:81], v[228:231], v[158:161], v[66:81]
	v_mfma_f32_32x32x16_bf16 v[98:113], v[232:235], v[142:145], v[98:113]
	v_mfma_f32_32x32x16_bf16 v[66:81], v[232:235], v[162:165], v[66:81]
	s_barrier
	v_add3_u32 v166, v248, v244, 0
	v_add3_u32 v167, v248, v245, 0
	v_add3_u32 v175, v248, v246, 0
	v_add3_u32 v185, v248, v247, 0
	ds_read_b128 v[130:133], v166 offset:16384
	ds_read_b128 v[134:137], v167 offset:16384
	ds_read_b128 v[138:141], v175 offset:16384
	ds_read_b128 v[142:145], v185 offset:16384
	ds_read_b128 v[146:149], v166 offset:20480
	ds_read_b128 v[150:153], v167 offset:20480
	ds_read_b128 v[158:161], v175 offset:20480
	ds_read_b128 v[162:165], v185 offset:20480
	s_waitcnt vmcnt(4)
	s_barrier
	s_waitcnt lgkmcnt(0)
	v_mfma_f32_32x32x16_bf16 v[50:65], v[176:179], v[130:133], v[50:65]
	v_mfma_f32_32x32x16_bf16 v[18:33], v[176:179], v[146:149], v[18:33]
	v_mfma_f32_32x32x16_bf16 v[50:65], v[180:183], v[134:137], v[50:65]
	v_mfma_f32_32x32x16_bf16 v[18:33], v[180:183], v[150:153], v[18:33]
	v_mfma_f32_32x32x16_bf16 v[50:65], v[186:189], v[138:141], v[50:65]
	v_mfma_f32_32x32x16_bf16 v[18:33], v[186:189], v[158:161], v[18:33]
	v_mfma_f32_32x32x16_bf16 v[50:65], v[190:193], v[142:145], v[50:65]
	v_mfma_f32_32x32x16_bf16 v[18:33], v[190:193], v[162:165], v[18:33]
	v_mfma_f32_32x32x16_bf16 v[34:49], v[194:197], v[130:133], v[34:49]
	v_mfma_f32_32x32x16_bf16 v[2:17], v[194:197], v[146:149], v[2:17]
	v_mfma_f32_32x32x16_bf16 v[34:49], v[198:201], v[134:137], v[34:49]
	v_mfma_f32_32x32x16_bf16 v[2:17], v[198:201], v[150:153], v[2:17]
	v_mfma_f32_32x32x16_bf16 v[34:49], v[228:231], v[138:141], v[34:49]
	v_mfma_f32_32x32x16_bf16 v[2:17], v[228:231], v[158:161], v[2:17]
	v_mfma_f32_32x32x16_bf16 v[34:49], v[232:235], v[142:145], v[34:49]
	v_mfma_f32_32x32x16_bf16 v[2:17], v[232:235], v[162:165], v[2:17]
	s_barrier
	v_add3_u32 v166, v249, v244, s21
	v_add3_u32 v167, v249, v245, s21
	v_add3_u32 v175, v249, v246, s21
	v_add3_u32 v185, v249, v247, s21
	ds_read_b128 v[176:179], v166 offset:32768
	ds_read_b128 v[180:183], v167 offset:32768
	ds_read_b128 v[186:189], v175 offset:32768
	ds_read_b128 v[190:193], v185 offset:32768
	v_add3_u32 v166, v248, v244, s21
	v_add3_u32 v167, v248, v245, s21
	v_add3_u32 v175, v248, v246, s21
	v_add3_u32 v185, v248, v247, s21
	ds_read_b128 v[130:133], v166
	ds_read_b128 v[134:137], v167
	ds_read_b128 v[138:141], v175
	ds_read_b128 v[142:145], v185
	ds_read_b128 v[146:149], v166 offset:4096
	ds_read_b128 v[150:153], v167 offset:4096
	ds_read_b128 v[158:161], v175 offset:4096
	ds_read_b128 v[162:165], v185 offset:4096
	s_waitcnt vmcnt(2)
	s_barrier
; template <bool SWAP>
; DI void gemm_mainloop(f32x16 (&acc)[4][2], const u16* __restrict__ A, int lda, int rlo, int rhi,
;                       const u16* __restrict__ B, int ldb, int K, char* lds, const u16* zero_line) {
;     ...
;   auto glds = [&](int kt, int st) {
;     char* as_ = lds + st * 65536 + tid * 16;
; #pragma unroll
;     for (int i = 0; i < 4; ++i) {
;       const int rr = lr + 64 * i;
;       const u16* srca = (rr >= rlo && rr < rhi) ? (ap + (ptrdiff_t)(64 * i) * lda + kt * 64) : (zero_line + lc * 8);
;       __builtin_amdgcn_global_load_lds((const unsigned*)srca, (lds_u32*)(as_ + i * 8192), 16, 0, 0);
;       __builtin_amdgcn_global_load_lds((const unsigned*)(bp + (ptrdiff_t)(64 * i) * ldb + kt * 64), (lds_u32*)(as_ + 32768 + i * 8192), 16, 0, 0);
;     }
;   };
;   const int sw = (r >> 1) & 7;
;   const int arow_off = (wm * 128 + r) * 128;
;   const int brow_off = 32768 + (wn * 64 + r) * 128;
;   __syncthreads();
;   glds(0, 0);
;   asm volatile("s_waitcnt vmcnt(0)" ::: "memory");
;     ...
;   for (int kt = 0; kt < nk; ++kt) {
;     const char* st = lds + (kt & 1) * 65536;
;     ldfrag(st, 0, 0);
;     mma(1);
;     pat_rd();
;     if (kt + 1 < nk) glds(kt + 1, (kt + 1) & 1);
;     ldfrag(st, 1, 1);
;     mma(0);
;     pat_rd();
;     ldfrag(st, 2, 0);
;     mma(1);
;     pat_rd();
;     ldfrag(st, 3, 1);
;     mma(0);
;     pat_rd();
;     asm volatile("s_waitcnt vmcnt(0)" ::: "memory");
;     __syncthreads();
;   }
;   mma(1);
	s_waitcnt lgkmcnt(0)
	v_mfma_f32_32x32x16_bf16 v[114:129], v[176:179], v[130:133], v[114:129]
	v_mfma_f32_32x32x16_bf16 v[82:97], v[176:179], v[146:149], v[82:97]
	v_mfma_f32_32x32x16_bf16 v[114:129], v[180:183], v[134:137], v[114:129]
	v_mfma_f32_32x32x16_bf16 v[82:97], v[180:183], v[150:153], v[82:97]
	v_mfma_f32_32x32x16_bf16 v[114:129], v[186:189], v[138:141], v[114:129]
	v_mfma_f32_32x32x16_bf16 v[82:97], v[186:189], v[158:161], v[82:97]
	v_mfma_f32_32x32x16_bf16 v[114:129], v[190:193], v[142:145], v[114:129]
	v_mfma_f32_32x32x16_bf16 v[82:97], v[190:193], v[162:165], v[82:97]
	s_barrier
	v_add3_u32 v166, v249, v244, s21
	v_add3_u32 v167, v249, v245, s21
	v_add3_u32 v175, v249, v246, s21
	v_add3_u32 v185, v249, v247, s21
	ds_read_b128 v[194:197], v166 offset:49152
	ds_read_b128 v[198:201], v167 offset:49152
	ds_read_b128 v[228:231], v175 offset:49152
	ds_read_b128 v[232:235], v185 offset:49152
	s_waitcnt vmcnt(0)
	s_barrier
	s_waitcnt lgkmcnt(0)
	v_mfma_f32_32x32x16_bf16 v[98:113], v[194:197], v[130:133], v[98:113]
	v_mfma_f32_32x32x16_bf16 v[66:81], v[194:197], v[146:149], v[66:81]
	v_mfma_f32_32x32x16_bf16 v[98:113], v[198:201], v[134:137], v[98:113]
	v_mfma_f32_32x32x16_bf16 v[66:81], v[198:201], v[150:153], v[66:81]
	v_mfma_f32_32x32x16_bf16 v[98:113], v[228:231], v[138:141], v[98:113]
	v_mfma_f32_32x32x16_bf16 v[66:81], v[228:231], v[158:161], v[66:81]
	v_mfma_f32_32x32x16_bf16 v[98:113], v[232:235], v[142:145], v[98:113]
	v_mfma_f32_32x32x16_bf16 v[66:81], v[232:235], v[162:165], v[66:81]
	s_barrier
	v_add3_u32 v166, v248, v244, s21
	v_add3_u32 v167, v248, v245, s21
	v_add3_u32 v175, v248, v246, s21
	v_add3_u32 v185, v248, v247, s21
	ds_read_b128 v[130:133], v166 offset:16384
	ds_read_b128 v[134:137], v167 offset:16384
	ds_read_b128 v[138:141], v175 offset:16384
	ds_read_b128 v[142:145], v185 offset:16384
	ds_read_b128 v[146:149], v166 offset:20480
	ds_read_b128 v[150:153], v167 offset:20480
	ds_read_b128 v[158:161], v175 offset:20480
	ds_read_b128 v[162:165], v185 offset:20480
	s_barrier
	s_waitcnt lgkmcnt(0)
	v_mfma_f32_32x32x16_bf16 v[50:65], v[176:179], v[130:133], v[50:65]
	v_mfma_f32_32x32x16_bf16 v[18:33], v[176:179], v[146:149], v[18:33]
	v_mfma_f32_32x32x16_bf16 v[50:65], v[180:183], v[134:137], v[50:65]
	v_mfma_f32_32x32x16_bf16 v[18:33], v[180:183], v[150:153], v[18:33]
	v_mfma_f32_32x32x16_bf16 v[50:65], v[186:189], v[138:141], v[50:65]
	v_mfma_f32_32x32x16_bf16 v[18:33], v[186:189], v[158:161], v[18:33]
	v_mfma_f32_32x32x16_bf16 v[50:65], v[190:193], v[142:145], v[50:65]
	v_mfma_f32_32x32x16_bf16 v[18:33], v[190:193], v[162:165], v[18:33]
	v_mfma_f32_32x32x16_bf16 v[34:49], v[194:197], v[130:133], v[34:49]
	v_mfma_f32_32x32x16_bf16 v[2:17], v[194:197], v[146:149], v[2:17]
	v_mfma_f32_32x32x16_bf16 v[34:49], v[198:201], v[134:137], v[34:49]
	v_mfma_f32_32x32x16_bf16 v[2:17], v[198:201], v[150:153], v[2:17]
	v_mfma_f32_32x32x16_bf16 v[34:49], v[228:231], v[138:141], v[34:49]
	v_mfma_f32_32x32x16_bf16 v[2:17], v[228:231], v[158:161], v[2:17]
	v_mfma_f32_32x32x16_bf16 v[34:49], v[232:235], v[142:145], v[34:49]
	v_mfma_f32_32x32x16_bf16 v[2:17], v[232:235], v[162:165], v[2:17]
	s_barrier
	s_cmp_eq_u32 s101, 0
	s_cbranch_scc0 .Lg8_u0u_p1
	s_barrier
.Lg8_u0u_p1:
	s_nop 7
	s_nop 7
	s_branch .Lg8_u0_join
.Lg8_u0_msk:
	s_add_u32 m0, s100, 0x8000
	s_nop 0
	global_load_lds_dwordx4 v240, s[22:23]
	v_add_u32_e32 v240, 0x80, v240
	s_add_u32 m0, s100, 0xa000
	s_nop 0
	global_load_lds_dwordx4 v242, s[22:23]
	v_add_u32_e32 v242, 0x80, v242
	s_add_u32 m0, s100, 0x0
	s_mov_b64 exec, s[10:11]
	global_load_lds_dwordx4 v236, s[18:19]
	s_mov_b64 exec, -1
	v_add_u32_e32 v236, 0x80, v236
	s_add_u32 m0, s100, 0x2000
	s_mov_b64 exec, s[14:15]
	global_load_lds_dwordx4 v238, s[18:19]
	s_mov_b64 exec, -1
	v_add_u32_e32 v238, 0x80, v238
	s_add_u32 m0, s100, 0xc000
	s_nop 0
	global_load_lds_dwordx4 v241, s[22:23]
	v_add_u32_e32 v241, 0x80, v241
	s_add_u32 m0, s100, 0xe000
	s_nop 0
	global_load_lds_dwordx4 v243, s[22:23]
	v_add_u32_e32 v243, 0x80, v243
	s_add_u32 m0, s100, 0x4000
	s_mov_b64 exec, s[12:13]
	global_load_lds_dwordx4 v237, s[18:19]
	s_mov_b64 exec, -1
	v_add_u32_e32 v237, 0x80, v237
	s_add_u32 m0, s100, 0x6000
	s_mov_b64 exec, s[16:17]
	global_load_lds_dwordx4 v239, s[18:19]
	s_mov_b64 exec, -1
	v_add_u32_e32 v239, 0x80, v239
	s_cmp_eq_u32 s101, 1
	s_cbranch_scc0 .Lg8_u0m_p0
	s_barrier

; template <int EPI>
; DI void phase_gemm(const Params& p, const GemmArgs& ga, char* lds) {
;     ...
;       __syncthreads();
;       constexpr int RS = 520;
;       {
;         char* wbase = lds + (wm * 128 + r) * RS + (wn * 64 + 4 * h) * 2;
; #pragma unroll
;         for (int mi = 0; mi < 4; ++mi)
; #pragma unroll
;           for (int ni = 0; ni < 2; ++ni)
; #pragma unroll
;             for (int j = 0; j < 4; ++j) {
;               u32x2 v = {pk_bf16(acc[mi][ni][4 * j], acc[mi][ni][4 * j + 1]), pk_bf16(acc[mi][ni][4 * j + 2], acc[mi][ni][4 * j + 3])};
;               *(u32x2*)(wbase + mi * 32 * RS + (ni * 32 + 8 * j) * 2) = v;
;             }
;       }
;       __syncthreads();
;       {
;         const int q4 = tid & 31, seg = tid >> 5;
;         const int ch = nt * 128 + 4 * q4;
;         const float* cw = p.ffn_conv_w + (size_t)ga.layer * 3 * 5632;
;         const float* cb = p.ffn_conv_b + (size_t)ga.layer * 5632;
;         float4 wg[3], wv[3];
; #pragma unroll
;         for (int t3 = 0; t3 < 3; ++t3) { wg[t3] = *(const float4*)(cw + t3 * 5632 + ch); wv[t3] = *(const float4*)(cw + t3 * 5632 + DFF + ch); }
;         const float4 bg = *(const float4*)(cb + ch);
;         const float4 bv = *(const float4*)(cb + DFF + ch);
;         const char* gbase = lds + q4 * 8;
;         const char* vbase = lds + 256 + q4 * 8;
;         const int R0 = 1 + seg * 16;
;         const int Rend = (R0 + 16 < 255) ? (R0 + 16) : 255;
;         auto ld4 = [&](const char* b_, int R) -> float4 {
;           const u32x2 u = *(const u32x2*)(b_ + R * RS);
;           float4 f = {__uint_as_float(u.x << 16), __uint_as_float(u.x & 0xffff0000u), __uint_as_float(u.y << 16), __uint_as_float(u.y & 0xffff0000u)};
;           return f;
;         };
;         float4 pg = ld4(gbase, R0 - 1), pvv = ld4(vbase, R0 - 1);
;         float4 cg_ = ld4(gbase, R0), cv_ = ld4(vbase, R0);
;         u16* Aout = (u16*)(p.ws + OFF_BIG) + (ptrdiff_t)(tokbase + pos0) * DFF + ch;
; #pragma unroll 4
;         for (int R = R0; R < Rend; ++R) {
;           const float4 ng = ld4(gbase, R + 1), nv = ld4(vbase, R + 1);
;           if (pos0 + R < S) {
.Lg8_u0_join:
.LBB0_61:
	v_add_u32_e32 v0, 0x4000, v173
	s_barrier
	s_nop 8
	v_cvt_pk_bf16_f32 v82, v82, v83
	v_cvt_pk_bf16_f32 v83, v84, v85
	v_cvt_pk_bf16_f32 v84, v86, v87
	v_cvt_pk_bf16_f32 v85, v88, v89
	ds_write2_b64 v0, v[82:83], v[84:85] offset0:32 offset1:34
	v_cvt_pk_bf16_f32 v82, v90, v91
	v_cvt_pk_bf16_f32 v83, v92, v93
	v_cvt_pk_bf16_f32 v66, v66, v67
	v_cvt_pk_bf16_f32 v67, v68, v69
	v_cvt_pk_bf16_f32 v68, v70, v71
	v_cvt_pk_bf16_f32 v69, v72, v73
	v_cvt_pk_bf16_f32 v84, v94, v95
	v_cvt_pk_bf16_f32 v85, v96, v97
	ds_write2_b64 v0, v[66:67], v[68:69] offset0:40 offset1:42
	v_cvt_pk_bf16_f32 v66, v74, v75
	v_cvt_pk_bf16_f32 v67, v76, v77
	v_cvt_pk_bf16_f32 v68, v78, v79
	v_cvt_pk_bf16_f32 v69, v80, v81
	ds_write2_b64 v0, v[82:83], v[84:85] offset0:36 offset1:38
	ds_write2_b64 v0, v[66:67], v[68:69] offset0:44 offset1:46
	v_cvt_pk_bf16_f32 v50, v50, v51
	v_cvt_pk_bf16_f32 v51, v52, v53
	v_cvt_pk_bf16_f32 v52, v54, v55
	v_cvt_pk_bf16_f32 v53, v56, v57
	v_add_u32_e32 v0, 0x8000, v173
	v_cvt_pk_bf16_f32 v34, v34, v35
	v_cvt_pk_bf16_f32 v35, v36, v37
	v_cvt_pk_bf16_f32 v36, v38, v39
	v_cvt_pk_bf16_f32 v37, v40, v41
	ds_write2_b64 v0, v[50:51], v[52:53] offset0:64 offset1:66
	v_cvt_pk_bf16_f32 v50, v58, v59
	v_cvt_pk_bf16_f32 v51, v60, v61
	v_cvt_pk_bf16_f32 v52, v62, v63
	v_cvt_pk_bf16_f32 v53, v64, v65
	ds_write2_b64 v0, v[34:35], v[36:37] offset0:72 offset1:74
	v_cvt_pk_bf16_f32 v34, v42, v43
	v_cvt_pk_bf16_f32 v35, v44, v45
	v_cvt_pk_bf16_f32 v36, v46, v47
	v_cvt_pk_bf16_f32 v37, v48, v49
	v_cvt_pk_bf16_f32 v114, v114, v115
	v_cvt_pk_bf16_f32 v115, v116, v117
	v_cvt_pk_bf16_f32 v116, v118, v119
	v_cvt_pk_bf16_f32 v117, v120, v121
	v_cvt_pk_bf16_f32 v98, v98, v99
	v_cvt_pk_bf16_f32 v99, v100, v101
	v_cvt_pk_bf16_f32 v100, v102, v103
	v_cvt_pk_bf16_f32 v101, v104, v105
	ds_write2_b64 v0, v[50:51], v[52:53] offset0:68 offset1:70
	ds_write2_b64 v0, v[34:35], v[36:37] offset0:76 offset1:78
	v_cvt_pk_bf16_f32 v18, v18, v19
	v_cvt_pk_bf16_f32 v19, v20, v21
	v_cvt_pk_bf16_f32 v20, v22, v23
	v_cvt_pk_bf16_f32 v21, v24, v25
	v_add_u32_e32 v0, 0xc000, v173
	v_cvt_pk_bf16_f32 v2, v2, v3
	v_cvt_pk_bf16_f32 v3, v4, v5
	v_cvt_pk_bf16_f32 v4, v6, v7
	v_cvt_pk_bf16_f32 v5, v8, v9
	ds_write2_b64 v173, v[114:115], v[116:117] offset1:2
	v_cvt_pk_bf16_f32 v114, v122, v123
	v_cvt_pk_bf16_f32 v115, v124, v125
	v_cvt_pk_bf16_f32 v116, v126, v127
	v_cvt_pk_bf16_f32 v117, v128, v129
	ds_write2_b64 v173, v[98:99], v[100:101] offset0:8 offset1:10
	v_cvt_pk_bf16_f32 v98, v106, v107
	v_cvt_pk_bf16_f32 v99, v108, v109
	v_cvt_pk_bf16_f32 v100, v110, v111
	v_cvt_pk_bf16_f32 v101, v112, v113
	ds_write2_b64 v0, v[18:19], v[20:21] offset0:96 offset1:98
	v_cvt_pk_bf16_f32 v18, v26, v27
	v_cvt_pk_bf16_f32 v19, v28, v29
	v_cvt_pk_bf16_f32 v20, v30, v31
	v_cvt_pk_bf16_f32 v21, v32, v33
	ds_write2_b64 v0, v[2:3], v[4:5] offset0:104 offset1:106
	v_cvt_pk_bf16_f32 v2, v10, v11
	v_cvt_pk_bf16_f32 v3, v12, v13
	v_cvt_pk_bf16_f32 v4, v14, v15
	v_cvt_pk_bf16_f32 v5, v16, v17
	ds_write2_b64 v173, v[114:115], v[116:117] offset0:4 offset1:6
	ds_write2_b64 v173, v[98:99], v[100:101] offset0:12 offset1:14
	ds_write2_b64 v0, v[18:19], v[20:21] offset0:100 offset1:102
	ds_write2_b64 v0, v[2:3], v[4:5] offset0:108 offset1:110
	s_waitcnt lgkmcnt(0)
	s_barrier
	s_and_saveexec_b64 s[12:13], vcc
	s_cbranch_execz .LBB0_54
	v_lshl_or_b32 v42, s28, 7, v157
	v_ashrrev_i32_e32 v43, 31, v42
	v_readlane_b32 s10, v253, 19
	v_lshlrev_b64 v[2:3], 2, v[42:43]
	v_readlane_b32 s11, v253, 20
	v_mov_b32_e32 v0, v169
	s_nop 0
	v_lshl_add_u64 v[4:5], s[10:11], 0, v[2:3]
	v_readlane_b32 s10, v253, 21
	v_readlane_b32 s11, v253, 22
	s_nop 1
	v_lshl_add_u64 v[6:7], s[10:11], 0, v[2:3]
	v_readlane_b32 s10, v253, 23
	v_readlane_b32 s11, v253, 24
	s_nop 1
	v_lshl_add_u64 v[10:11], s[10:11], 0, v[2:3]
	v_readlane_b32 s10, v253, 25
	v_readlane_b32 s11, v253, 26
	s_nop 1
	v_lshl_add_u64 v[14:15], s[10:11], 0, v[2:3]
	v_readlane_b32 s10, v253, 27
	v_readlane_b32 s11, v253, 28
	s_nop 1
	v_lshl_add_u64 v[18:19], s[10:11], 0, v[2:3]
	v_readlane_b32 s10, v253, 29
	v_readlane_b32 s11, v253, 30
	s_nop 1
	v_lshl_add_u64 v[22:23], s[10:11], 0, v[2:3]
	v_readlane_b32 s10, v253, 31
	v_readlane_b32 s11, v253, 32
	s_nop 1
	v_lshl_add_u64 v[26:27], s[10:11], 0, v[2:3]
	v_readlane_b32 s10, v253, 33
	v_readlane_b32 s11, v253, 34
	s_nop 1
	v_lshl_add_u64 v[30:31], s[10:11], 0, v[2:3]
	global_load_dwordx4 v[2:5], v[4:5], off
	s_nop 0
	global_load_dwordx4 v[6:9], v[6:7], off
	s_nop 0
	global_load_dwordx4 v[10:13], v[10:11], off
	s_nop 0
	global_load_dwordx4 v[14:17], v[14:15], off
	s_nop 0
	global_load_dwordx4 v[18:21], v[18:19], off
	s_nop 0
	global_load_dwordx4 v[22:25], v[22:23], off
	s_nop 0
	global_load_dwordx4 v[26:29], v[26:27], off
	s_nop 0
	global_load_dwordx4 v[30:33], v[30:31], off
	ds_read2_b64 v[36:39], v174 offset0:65 offset1:97
	ds_read2_b64 v[46:49], v174 offset1:32
	s_waitcnt lgkmcnt(1)
	v_and_b32_e32 v35, 0xffff0000, v37
	v_lshlrev_b32_e32 v34, 16, v37
	v_and_b32_e32 v41, 0xffff0000, v36
	v_lshlrev_b32_e32 v40, 16, v36
	v_lshlrev_b32_e32 v36, 16, v39
	v_and_b32_e32 v37, 0xffff0000, v39
	s_waitcnt lgkmcnt(0)
	v_lshlrev_b32_e32 v50, 16, v49
	v_and_b32_e32 v51, 0xffff0000, v49
	v_lshlrev_b32_e32 v52, 16, v47
	v_and_b32_e32 v53, 0xffff0000, v47
	v_lshlrev_b32_e32 v44, 16, v38
	v_and_b32_e32 v45, 0xffff0000, v38
	v_lshlrev_b32_e32 v54, 16, v48
	v_and_b32_e32 v55, 0xffff0000, v48
	v_lshlrev_b32_e32 v56, 16, v46
	v_and_b32_e32 v57, 0xffff0000, v46
	v_lshlrev_b64 v[46:47], 1, v[42:43]
	s_and_saveexec_b64 s[14:15], s[6:7]
	s_cbranch_execz .LBB0_68
	s_add_i32 s10, s27, -2
	v_mad_i64_i32 v[38:39], s[10:11], s10, v216, v[46:47]
	v_lshl_add_u64 v[38:39], v[154:155], 0, v[38:39]
	s_mov_b64 s[16:17], 0
	v_mov_b32_e32 v0, v171
	v_mov_b32_e32 v62, v172
	v_mov_b32_e32 v64, v168
	s_mov_b64 s[22:23], 0x1600
	s_waitcnt vmcnt(0)
	s_branch .LBB0_65

; DI int opaque_tid() { int t = threadIdx.x; asm volatile("" : "+v"(t)); return t; }
; template <bool SWAP>
; DI void gemm_mainloop(f32x16 (&acc)[4][2], const u16* __restrict__ A, int lda, int rlo, int rhi,
;                       const u16* __restrict__ B, int ldb, int K, char* lds, const u16* zero_line) {
;   const int tid = opaque_tid(), lane = tid & 63, w = tid >> 6;
;   const int wm = w >> 2, wn = w & 3;
;   const int h = lane >> 5, r = lane & 31;
;   const int lr = tid >> 3, lc = tid & 7;
; #pragma unroll
;   for (int mi = 0; mi < 4; ++mi)
; #pragma unroll
;     for (int ni = 0; ni < 2; ++ni)
; #pragma unroll
;       for (int i = 0; i < 16; ++i) acc[mi][ni][i] = 0.f;
;   const int gch = (lc ^ ((lr >> 1) & 7)) * 8;
;   const u16* ap = A + (ptrdiff_t)lr * lda + gch;
;   const u16* bp = B + (ptrdiff_t)lr * ldb + gch;
; template <int EPI>
; DI void phase_gemm(const Params& p, const GemmArgs& ga, char* lds) {
;     ...
;   for (int it = 0; it * (int)gridDim.x < total; ++it) {
;     const int lt = logical_index(it);
;     if (lt >= total) continue;
;     int mt, nt;
;     tile_mn(lt, Mt, ga.Nt, mt, nt);
;     int bb, tokbase, S, pos0, rlo = 0, rhi = 256;
;     if (EPI == EPI_UP) {
;       bb = 0; tokbase = 0; S = NTOK;
;       pos0 = 254 * mt - 1;
;       rlo = (mt == 0) ? 1 : 0;
;       rhi = NTOK - pos0; if (rhi > 256) rhi = 256;
;     } else {
;       seq_of_token(mt * 256, bb, tokbase, S);
;       pos0 = mt * 256 - tokbase;
;     }
;     const u16* A = ga.A + (ptrdiff_t)(tokbase + pos0) * ga.lda;
;     const u16* B = ga.Bt + (size_t)(nt * 256) * ga.K;
.LBB0_167:
	s_add_i32 s30, s10, s25
	s_cmpk_gt_i32 s30, 0x10ab
	s_cbranch_scc1 .LBB0_166
	s_mul_hi_i32 s10, s30, 0x2e8ba2e9
	s_lshr_b32 s11, s10, 31
	s_ashr_i32 s10, s10, 5
	s_add_i32 s31, s10, s11
	s_lshl_b32 s10, s31, 3
	s_sub_i32 s11, 0xc2, s10
	s_min_u32 s11, s11, 8
	v_cvt_f32_ubyte0_e32 v0, s11
	v_rcp_iflag_f32_e32 v0, v0
	s_sub_i32 s15, 0, s11
	s_mul_i32 s12, s31, 0xffffff50
	s_add_i32 s12, s12, s30
	v_mul_f32_e32 v0, 0x4f7ffffe, v0
	v_cvt_u32_f32_e32 v0, v0
	s_abs_i32 s14, s12
	s_ashr_i32 s13, s12, 31
	s_waitcnt vmcnt(5)
	v_mov_b32_e32 v13, v204
	v_readfirstlane_b32 s16, v0
	s_mul_i32 s15, s15, s16
	s_mul_hi_u32 s15, s16, s15
	s_add_i32 s16, s16, s15
	s_mul_hi_u32 s15, s14, s16
	s_mul_i32 s16, s15, s11
	s_sub_i32 s14, s14, s16
	s_add_i32 s16, s15, 1
	s_sub_i32 s17, s14, s11
	s_cmp_ge_u32 s14, s11
	s_cselect_b32 s15, s16, s15
	s_cselect_b32 s14, s17, s14
	s_add_i32 s16, s15, 1
	s_cmp_ge_u32 s14, s11
	s_cselect_b32 s14, s16, s15
	s_xor_b32 s14, s14, s13
	s_sub_i32 s28, s14, s13
	s_mul_i32 s34, s28, s11
	s_add_i32 s14, s12, s10
	s_sub_i32 s27, s14, s34
	s_mulk_i32 s27, 0xfe
	s_lshl_b32 s10, s28, 8
	s_add_i32 s20, s27, -1
	s_ashr_i32 s11, s10, 31
	s_ashr_i32 s21, s20, 31
	s_lshl_b64 s[22:23], s[10:11], 11
	v_readlane_b32 s10, v253, 47
	v_readlane_b32 s11, v253, 48
	s_add_u32 s10, s10, s22
	s_addc_u32 s11, s11, s23
	s_lshl_b64 s[12:13], s[20:21], 11
	s_add_u32 s12, s90, s12
	v_ashrrev_i32_e32 v2, 3, v13
	s_waitcnt vmcnt(4)
	v_lshrrev_b32_e32 v15, 1, v2
	s_addc_u32 s13, s91, s13
	s_sub_i32 s15, 0xc001, s27
	v_xor_b32_e32 v0, v15, v13
	v_ashrrev_i32_e32 v3, 31, v2
	s_min_i32 s18, s15, 0x100
	v_lshlrev_b64 v[4:5], 11, v[2:3]
	v_lshlrev_b32_e32 v0, 4, v0
	s_cmp_eq_u32 s14, s34
	v_and_b32_e32 v10, 31, v13
	v_lshl_add_u64 v[6:7], s[12:13], 0, v[4:5]
	v_and_b32_e32 v0, 0x70, v0
	v_lshl_add_u64 v[8:9], s[10:11], 0, v[4:5]
	v_lshrrev_b32_e32 v16, 1, v13
	s_cselect_b64 s[14:15], -1, 0
	v_lshl_add_u64 v[6:7], v[6:7], 0, v[0:1]
	v_lshl_add_u64 v[8:9], v[8:9], 0, v[0:1]
	v_and_or_b32 v0, v16, s51, v10
	v_cndmask_b32_e64 v12, 0, 1, s[14:15]
	v_lshlrev_b32_e32 v175, 7, v0
	v_lshlrev_b32_e32 v0, 7, v13
	v_lshlrev_b32_e32 v177, 4, v13
	v_and_b32_e32 v176, 0x6f80, v0
	v_cmp_ge_i32_e64 s[10:11], v2, v12
	v_cmp_gt_i32_e64 s[12:13], s18, v2
	v_and_b32_e32 v0, 0x70, v177
	v_add_u32_e32 v178, 0x8000, v177
	v_lshl_add_u64 v[158:159], s[80:81], 0, v[0:1]
	s_and_b64 s[10:11], s[10:11], s[12:13]
	v_readfirstlane_b32 s12, v177
	v_cndmask_b32_e64 v11, v159, v7, s[10:11]
	v_cndmask_b32_e64 v10, v158, v6, s[10:11]
	s_mov_b32 m0, s12
	v_readfirstlane_b32 s12, v178
	v_add_u32_e32 v0, 64, v2
	s_barrier
	s_mov_b32 m0, s12
	v_cmp_ge_i32_e64 s[12:13], v0, v12
	v_cmp_gt_i32_e64 s[14:15], s18, v0
	s_mov_b64 s[16:17], 0x20000
	v_add_u32_e32 v0, 0x2000, v177
	v_lshl_add_u64 v[10:11], v[6:7], 0, s[16:17]
	s_and_b64 s[12:13], s[12:13], s[14:15]
	v_readfirstlane_b32 s14, v0
	v_add_u32_e32 v179, 0xa000, v177
	v_cndmask_b32_e64 v11, v159, v11, s[12:13]
	v_cndmask_b32_e64 v10, v158, v10, s[12:13]
	s_mov_b32 m0, s14
	v_readfirstlane_b32 s14, v179
	v_add_u32_e32 v3, 0x80, v2
	v_lshl_add_u64 v[10:11], v[8:9], 0, s[16:17]
	s_mov_b32 m0, s14
	v_cmp_ge_i32_e64 s[14:15], v3, v12
	v_cmp_gt_i32_e64 s[16:17], s18, v3
	s_mov_b64 s[36:37], 0x40000
	v_add_u32_e32 v180, 0x4000, v177
	v_lshl_add_u64 v[10:11], v[6:7], 0, s[36:37]
	s_and_b64 s[14:15], s[14:15], s[16:17]
	v_readfirstlane_b32 s16, v180
	v_add_u32_e32 v181, 0xc000, v177
	v_cndmask_b32_e64 v11, v159, v11, s[14:15]
	v_cndmask_b32_e64 v10, v158, v10, s[14:15]
	s_mov_b32 m0, s16
	v_readfirstlane_b32 s16, v181
	v_add_u32_e32 v2, 0xc0, v2
	v_lshl_add_u64 v[10:11], v[8:9], 0, s[36:37]
	s_mov_b32 m0, s16
	v_cmp_ge_i32_e64 s[16:17], v2, v12
	v_cmp_gt_i32_e64 s[18:19], s18, v2
	s_mov_b64 s[36:37], 0x60000
	v_add_u32_e32 v182, 0x6000, v177
	v_lshl_add_u64 v[2:3], v[6:7], 0, s[36:37]
	s_and_b64 s[16:17], s[16:17], s[18:19]
	v_readfirstlane_b32 s18, v182
	v_add_u32_e32 v183, 0xe000, v177
	v_cndmask_b32_e64 v3, v159, v3, s[16:17]
	v_cndmask_b32_e64 v2, v158, v2, s[16:17]
	s_mov_b32 m0, s18
	v_readfirstlane_b32 s18, v183
	v_lshl_add_u64 v[2:3], v[8:9], 0, s[36:37]
	s_mov_b32 m0, s18
	s_sub_i32 s18, s30, s34
	s_mulk_i32 s31, 0xa8
	v_bfe_u32 v14, v13, 5, 1
	s_sub_i32 s18, s18, s31
	v_bfe_u32 v17, v13, 1, 3
	v_bitop3_b32 v2, v16, v14, 7 bitop3:0x6c
	s_mulk_i32 s18, 0xfe
	v_lshlrev_b32_e32 v185, 4, v2
	v_bitop3_b32 v2, v14, v17, 2 bitop3:0x36
	s_add_i32 s18, s18, -2
	v_lshlrev_b32_e32 v186, 4, v2
	v_bitop3_b32 v2, v14, v17, 4 bitop3:0x36
	s_ashr_i32 s19, s18, 31
	v_lshlrev_b32_e32 v187, 4, v2
	v_bitop3_b32 v2, v14, v17, 6 bitop3:0x36
	s_lshl_b64 s[18:19], s[18:19], 11
	v_bitop3_b32 v6, v15, 7, v13 bitop3:0x48
	v_lshlrev_b32_e32 v188, 4, v2
	v_lshl_add_u64 v[2:3], v[4:5], 0, s[18:19]
	v_lshlrev_b32_e32 v6, 4, v6
	v_or_b32_e32 v2, v2, v6
	v_lshl_add_u64 v[160:161], s[70:71], 0, v[2:3]
	v_lshl_add_u64 v[2:3], v[4:5], 0, s[22:23]
	s_waitcnt vmcnt(0)
	v_or_b32_e32 v2, v2, v6
	v_lshl_add_u64 v[162:163], s[70:71], 0, v[2:3]
	v_mov_b32_e32 v130, 0
	v_mov_b32_e32 v2, 0
	s_mov_b32 s29, 1
	v_add_u32_e32 v189, 0x10000, v177
	v_add_u32_e32 v190, 0x18000, v177
	v_add_u32_e32 v191, 0x12000, v177
	v_add_u32_e32 v192, 0x1a000, v177
	v_add_u32_e32 v193, 0x14000, v177
	v_add_u32_e32 v194, 0x1c000, v177
	v_add_u32_e32 v195, 0x16000, v177
	v_add_u32_e32 v196, 0x1e000, v177
	v_add_u32_e32 v197, 0x10000, v175
	v_or_b32_e32 v198, 0x10000, v176
	s_mov_b64 s[18:19], 0
	v_mov_b32_e32 v3, v2
	v_mov_b32_e32 v4, v2
	v_mov_b32_e32 v5, v2
	v_mov_b32_e32 v6, v2
	v_mov_b32_e32 v7, v2
	v_mov_b32_e32 v8, v2
	v_mov_b32_e32 v9, v2
	v_mov_b32_e32 v10, v2
	v_mov_b32_e32 v11, v2
	v_mov_b32_e32 v12, v2
	v_mov_b32_e32 v13, v2
	v_mov_b32_e32 v14, v2
	v_mov_b32_e32 v15, v2
	v_mov_b32_e32 v16, v2
	v_mov_b32_e32 v17, v2
	s_waitcnt vmcnt(0)
; template <bool SWAP>
; DI void gemm_mainloop(f32x16 (&acc)[4][2], const u16* __restrict__ A, int lda, int rlo, int rhi,
;                       const u16* __restrict__ B, int ldb, int K, char* lds, const u16* zero_line) {
;     ...
; #pragma unroll
;   for (int mi = 0; mi < 4; ++mi)
; #pragma unroll
;     for (int ni = 0; ni < 2; ++ni)
; #pragma unroll
;       for (int i = 0; i < 16; ++i) acc[mi][ni][i] = 0.f;
;   const int gch = (lc ^ ((lr >> 1) & 7)) * 8;
;   const u16* ap = A + (ptrdiff_t)lr * lda + gch;
;   const u16* bp = B + (ptrdiff_t)lr * ldb + gch;
;   const int nk = K >> 6;
;   typedef __attribute__((address_space(3))) unsigned lds_u32;
;   auto glds = [&](int kt, int st) {
;     char* as_ = lds + st * 65536 + tid * 16;
; #pragma unroll
;     for (int i = 0; i < 4; ++i) {
;       const int rr = lr + 64 * i;
;       const u16* srca = (rr >= rlo && rr < rhi) ? (ap + (ptrdiff_t)(64 * i) * lda + kt * 64) : (zero_line + lc * 8);
;       __builtin_amdgcn_global_load_lds((const unsigned*)srca, (lds_u32*)(as_ + i * 8192), 16, 0, 0);
;       __builtin_amdgcn_global_load_lds((const unsigned*)(bp + (ptrdiff_t)(64 * i) * ldb + kt * 64), (lds_u32*)(as_ + 32768 + i * 8192), 16, 0, 0);
;     }
;   };
;   const int sw = (r >> 1) & 7;
;   const int arow_off = (wm * 128 + r) * 128;
;   const int brow_off = 32768 + (wn * 64 + r) * 128;
;   __syncthreads();
;   glds(0, 0);
;   asm volatile("s_waitcnt vmcnt(0)" ::: "memory");
;   __syncthreads();
	v_mov_b32_e32 v18, v2
	v_mov_b32_e32 v19, v2
	v_mov_b32_e32 v20, v2
	v_mov_b32_e32 v21, v2
	v_mov_b32_e32 v22, v2
	v_mov_b32_e32 v23, v2
	v_mov_b32_e32 v24, v2
	v_mov_b32_e32 v25, v2
	v_mov_b32_e32 v26, v2
	v_mov_b32_e32 v27, v2
	v_mov_b32_e32 v28, v2
	v_mov_b32_e32 v29, v2
	v_mov_b32_e32 v30, v2
	v_mov_b32_e32 v31, v2
	v_mov_b32_e32 v32, v2
	v_mov_b32_e32 v33, v2
	v_mov_b32_e32 v34, v2
	v_mov_b32_e32 v35, v2
	v_mov_b32_e32 v36, v2
	v_mov_b32_e32 v37, v2
	v_mov_b32_e32 v38, v2
	v_mov_b32_e32 v39, v2
	v_mov_b32_e32 v40, v2
	v_mov_b32_e32 v41, v2
	v_mov_b32_e32 v42, v2
	v_mov_b32_e32 v43, v2
	v_mov_b32_e32 v44, v2
	v_mov_b32_e32 v45, v2
	v_mov_b32_e32 v46, v2
	v_mov_b32_e32 v47, v2
	v_mov_b32_e32 v48, v2
	v_mov_b32_e32 v49, v2
	v_mov_b32_e32 v50, v2
	v_mov_b32_e32 v51, v2
	v_mov_b32_e32 v52, v2
	v_mov_b32_e32 v53, v2
	v_mov_b32_e32 v54, v2
	v_mov_b32_e32 v55, v2
	v_mov_b32_e32 v56, v2
	v_mov_b32_e32 v57, v2
	v_mov_b32_e32 v58, v2
	v_mov_b32_e32 v59, v2
	v_mov_b32_e32 v60, v2
	v_mov_b32_e32 v61, v2
	v_mov_b32_e32 v62, v2
	v_mov_b32_e32 v63, v2
	v_mov_b32_e32 v64, v2
	v_mov_b32_e32 v65, v2
	v_mov_b32_e32 v66, v2
	v_mov_b32_e32 v67, v2
	v_mov_b32_e32 v68, v2
	v_mov_b32_e32 v69, v2
	v_mov_b32_e32 v70, v2
	v_mov_b32_e32 v71, v2
	v_mov_b32_e32 v72, v2
	v_mov_b32_e32 v73, v2
	v_mov_b32_e32 v74, v2
	v_mov_b32_e32 v75, v2
	v_mov_b32_e32 v76, v2
	v_mov_b32_e32 v77, v2
	v_mov_b32_e32 v78, v2
	v_mov_b32_e32 v79, v2
	v_mov_b32_e32 v80, v2
	v_mov_b32_e32 v81, v2
	v_mov_b32_e32 v82, v2
	v_mov_b32_e32 v83, v2
	v_mov_b32_e32 v84, v2
	v_mov_b32_e32 v85, v2
	v_mov_b32_e32 v86, v2
	v_mov_b32_e32 v87, v2
	v_mov_b32_e32 v88, v2
	v_mov_b32_e32 v89, v2
	v_mov_b32_e32 v90, v2
	v_mov_b32_e32 v91, v2
	v_mov_b32_e32 v92, v2
	v_mov_b32_e32 v93, v2
	v_mov_b32_e32 v94, v2
	v_mov_b32_e32 v95, v2
	v_mov_b32_e32 v96, v2
	v_mov_b32_e32 v97, v2
	v_mov_b32_e32 v98, v2
	v_mov_b32_e32 v99, v2
	v_mov_b32_e32 v100, v2
	v_mov_b32_e32 v101, v2
	v_mov_b32_e32 v102, v2
	v_mov_b32_e32 v103, v2
	v_mov_b32_e32 v104, v2
	v_mov_b32_e32 v105, v2
	v_mov_b32_e32 v106, v2
	v_mov_b32_e32 v107, v2
	v_mov_b32_e32 v108, v2
	v_mov_b32_e32 v109, v2
	v_mov_b32_e32 v110, v2
	v_mov_b32_e32 v111, v2
	v_mov_b32_e32 v112, v2
	v_mov_b32_e32 v113, v2
	v_mov_b32_e32 v114, v2
	v_mov_b32_e32 v115, v2
	v_mov_b32_e32 v116, v2
	v_mov_b32_e32 v117, v2
	v_mov_b32_e32 v118, v2
	v_mov_b32_e32 v119, v2
	v_mov_b32_e32 v120, v2
	v_mov_b32_e32 v121, v2
	v_mov_b32_e32 v122, v2
	v_mov_b32_e32 v123, v2
	v_mov_b32_e32 v124, v2
	v_mov_b32_e32 v125, v2
	v_mov_b32_e32 v126, v2
	v_mov_b32_e32 v127, v2
	v_mov_b32_e32 v128, v2
	v_mov_b32_e32 v129, v2
	v_mov_b32_e32 v131, v130
	v_mov_b32_e32 v132, v130
	v_mov_b32_e32 v133, v130
	v_mov_b32_e32 v134, v130
	v_mov_b32_e32 v135, v130
	v_mov_b32_e32 v136, v130
	v_mov_b32_e32 v137, v130
	v_mov_b32_e32 v138, v130
	v_mov_b32_e32 v139, v130
	v_mov_b32_e32 v140, v130
	v_mov_b32_e32 v141, v130
	v_mov_b32_e32 v142, v130
	v_mov_b32_e32 v143, v130
	v_mov_b32_e32 v144, v130
	v_mov_b32_e32 v145, v130
	v_mov_b32_e32 v146, v130
	v_mov_b32_e32 v147, v130
	v_mov_b32_e32 v148, v130
	v_mov_b32_e32 v149, v130
	v_mov_b32_e32 v150, v130
	v_mov_b32_e32 v151, v130
	v_mov_b32_e32 v152, v130
	v_mov_b32_e32 v153, v130
	s_mov_b64 s[30:31], 0x37f8900
	s_waitcnt lgkmcnt(0)
	s_barrier
	s_add_i32 s18, s27, -1
	s_ashr_i32 s19, s18, 31
	s_lshl_b64 s[18:19], s[18:19], 11
	s_add_u32 s18, s90, s18
	s_addc_u32 s19, s91, s19
	v_readlane_b32 s22, v253, 47
	v_readlane_b32 s23, v253, 48
	s_lshl_b32 s21, s28, 19
	s_add_u32 s22, s22, s21
	s_addc_u32 s23, s23, 0
	v_and_b32_e32 v130, 63, v204
	v_lshrrev_b32_e32 v131, 6, v204
	v_lshrrev_b32_e32 v132, 3, v204
	v_lshrrev_b32_e32 v0, 4, v130
	v_lshl_add_u32 v0, v131, 2, v0
	v_xor_b32_e32 v0, v0, v130
	v_and_b32_e32 v0, 7, v0
	v_lshlrev_b32_e32 v133, 4, v0
	v_lshl_add_u32 v236, v132, 11, v133
	v_add_u32_e32 v237, 0x20000, v236
	v_add_u32_e32 v238, 0x40000, v236
	v_add_u32_e32 v239, 0x60000, v236
	v_and_b32_e32 v0, 31, v132
	v_lshrrev_b32_e32 v130, 5, v132
	v_lshl_add_u32 v0, v130, 6, v0
	v_lshl_add_u32 v240, v0, 11, v133
	v_add_u32_e32 v241, 0x10000, v240
	v_add_u32_e32 v242, 0x40000, v240
	v_add_u32_e32 v243, 0x50000, v240
	v_and_b32_e32 v132, 31, v204
	v_lshrrev_b32_e32 v0, 2, v131
	v_lshl_add_u32 v0, v0, 6, v132
	v_lshlrev_b32_e32 v248, 7, v0
	v_and_b32_e32 v0, 3, v131
	v_lshl_add_u32 v0, v0, 5, v132
	v_lshlrev_b32_e32 v249, 7, v0
	v_bfe_u32 v0, v204, 5, 1
	v_bfe_u32 v130, v132, 1, 3
	v_or_b32_e32 v133, 0, v0
	v_xor_b32_e32 v133, v133, v130
	v_lshlrev_b32_e32 v244, 4, v133
	v_or_b32_e32 v133, 2, v0
	v_xor_b32_e32 v133, v133, v130
	v_lshlrev_b32_e32 v245, 4, v133
	v_or_b32_e32 v133, 4, v0
	v_xor_b32_e32 v133, v133, v130
	v_lshlrev_b32_e32 v246, 4, v133
	v_or_b32_e32 v133, 6, v0
	v_xor_b32_e32 v133, v133, v130
	v_lshlrev_b32_e32 v247, 4, v133
	v_lshlrev_b32_e32 v131, 10, v131
	s_nop 0
	v_readfirstlane_b32 s100, v131
	v_mov_b32_e32 v146, 0
	v_mov_b32_e32 v147, 0
	v_mov_b32_e32 v148, 0
	v_mov_b32_e32 v149, 0
	v_lshlrev_b32_e32 v130, 4, v204
	v_add_u32_e32 v132, 0x10000, v130
	s_not_b64 exec, s[10:11]
	ds_write_b128 v130, v[146:149]
	ds_write_b128 v132, v[146:149]
	s_not_b64 exec, s[12:13]
	ds_write_b128 v130, v[146:149] offset:16384
	ds_write_b128 v132, v[146:149] offset:16384
	s_not_b64 exec, s[14:15]
	ds_write_b128 v130, v[146:149] offset:8192
	ds_write_b128 v132, v[146:149] offset:8192
	s_not_b64 exec, s[16:17]
	ds_write_b128 v130, v[146:149] offset:24576
	ds_write_b128 v132, v[146:149] offset:24576
	s_mov_b64 exec, -1
	s_mov_b32 s29, 0
	s_mov_b32 s21, 0x10000
	s_waitcnt lgkmcnt(0)
	s_cmp_eq_u32 s27, 0
	s_cbranch_scc1 .Lg8_u1_msk
	s_cmp_gt_i32 s20, 0xbf00
	s_cbranch_scc1 .Lg8_u1_msk
	s_add_u32 m0, s100, 0x8000
	s_nop 0
	global_load_lds_dwordx4 v240, s[22:23]
	v_add_u32_e32 v240, 0x80, v240
	s_add_u32 m0, s100, 0xa000
	s_nop 0
	global_load_lds_dwordx4 v242, s[22:23]
	v_add_u32_e32 v242, 0x80, v242
	s_add_u32 m0, s100, 0x0
	s_nop 0
	global_load_lds_dwordx4 v236, s[18:19]
	v_add_u32_e32 v236, 0x80, v236
	s_add_u32 m0, s100, 0x2000
	s_nop 0
	global_load_lds_dwordx4 v238, s[18:19]
	v_add_u32_e32 v238, 0x80, v238
	s_add_u32 m0, s100, 0xc000
	s_nop 0
	global_load_lds_dwordx4 v241, s[22:23]
	v_add_u32_e32 v241, 0x80, v241
	s_add_u32 m0, s100, 0xe000
	s_nop 0
	global_load_lds_dwordx4 v243, s[22:23]
	v_add_u32_e32 v243, 0x80, v243
	s_add_u32 m0, s100, 0x4000
	s_nop 0
	global_load_lds_dwordx4 v237, s[18:19]
	v_add_u32_e32 v237, 0x80, v237
	s_add_u32 m0, s100, 0x6000
	s_nop 0
	global_load_lds_dwordx4 v239, s[18:19]
	v_add_u32_e32 v239, 0x80, v239
	s_cmp_eq_u32 s101, 1
	s_cbranch_scc0 .Lg8_u1u_p0
	s_barrier

; template <int EPI>
; DI void phase_gemm(const Params& p, const GemmArgs& ga, char* lds) {
;     ...
;       __syncthreads();
;       constexpr int RS = 520;
;       {
;         char* wbase = lds + (wm * 128 + r) * RS + (wn * 64 + 4 * h) * 2;
; #pragma unroll
;         for (int mi = 0; mi < 4; ++mi)
; #pragma unroll
;           for (int ni = 0; ni < 2; ++ni)
; #pragma unroll
;             for (int j = 0; j < 4; ++j) {
;               u32x2 v = {pk_bf16(acc[mi][ni][4 * j], acc[mi][ni][4 * j + 1]), pk_bf16(acc[mi][ni][4 * j + 2], acc[mi][ni][4 * j + 3])};
;               *(u32x2*)(wbase + mi * 32 * RS + (ni * 32 + 8 * j) * 2) = v;
;             }
;       }
;       __syncthreads();
;       {
;         const int q4 = tid & 31, seg = tid >> 5;
;         const int ch = nt * 128 + 4 * q4;
;         const float* cw = p.ffn_conv_w + (size_t)ga.layer * 3 * 5632;
;         const float* cb = p.ffn_conv_b + (size_t)ga.layer * 5632;
;         float4 wg[3], wv[3];
; #pragma unroll
;         for (int t3 = 0; t3 < 3; ++t3) { wg[t3] = *(const float4*)(cw + t3 * 5632 + ch); wv[t3] = *(const float4*)(cw + t3 * 5632 + DFF + ch); }
;         const float4 bg = *(const float4*)(cb + ch);
;         const float4 bv = *(const float4*)(cb + DFF + ch);
;         const char* gbase = lds + q4 * 8;
;         const char* vbase = lds + 256 + q4 * 8;
;         const int R0 = 1 + seg * 16;
;         const int Rend = (R0 + 16 < 255) ? (R0 + 16) : 255;
;         auto ld4 = [&](const char* b_, int R) -> float4 {
;           const u32x2 u = *(const u32x2*)(b_ + R * RS);
;           float4 f = {__uint_as_float(u.x << 16), __uint_as_float(u.x & 0xffff0000u), __uint_as_float(u.y << 16), __uint_as_float(u.y & 0xffff0000u)};
;           return f;
;         };
;         float4 pg = ld4(gbase, R0 - 1), pvv = ld4(vbase, R0 - 1);
;         float4 cg_ = ld4(gbase, R0), cv_ = ld4(vbase, R0);
;         u16* Aout = (u16*)(p.ws + OFF_BIG) + (ptrdiff_t)(tokbase + pos0) * DFF + ch;
; #pragma unroll 4
;         for (int R = R0; R < Rend; ++R) {
;           const float4 ng = ld4(gbase, R + 1), nv = ld4(vbase, R + 1);
;           if (pos0 + R < S) {
.Lg8_u1_join:
.LBB0_172:
	v_add_u32_e32 v0, 0x4000, v173
	s_barrier
	s_nop 8
	v_cvt_pk_bf16_f32 v82, v82, v83
	v_cvt_pk_bf16_f32 v83, v84, v85
	v_cvt_pk_bf16_f32 v84, v86, v87
	v_cvt_pk_bf16_f32 v85, v88, v89
	ds_write2_b64 v0, v[82:83], v[84:85] offset0:32 offset1:34
	v_cvt_pk_bf16_f32 v82, v90, v91
	v_cvt_pk_bf16_f32 v83, v92, v93
	v_cvt_pk_bf16_f32 v66, v66, v67
	v_cvt_pk_bf16_f32 v67, v68, v69
	v_cvt_pk_bf16_f32 v68, v70, v71
	v_cvt_pk_bf16_f32 v69, v72, v73
	v_cvt_pk_bf16_f32 v84, v94, v95
	v_cvt_pk_bf16_f32 v85, v96, v97
	ds_write2_b64 v0, v[66:67], v[68:69] offset0:40 offset1:42
	v_cvt_pk_bf16_f32 v66, v74, v75
	v_cvt_pk_bf16_f32 v67, v76, v77
	v_cvt_pk_bf16_f32 v68, v78, v79
	v_cvt_pk_bf16_f32 v69, v80, v81
	ds_write2_b64 v0, v[82:83], v[84:85] offset0:36 offset1:38
	ds_write2_b64 v0, v[66:67], v[68:69] offset0:44 offset1:46
	v_cvt_pk_bf16_f32 v50, v50, v51
	v_cvt_pk_bf16_f32 v51, v52, v53
	v_cvt_pk_bf16_f32 v52, v54, v55
	v_cvt_pk_bf16_f32 v53, v56, v57
	v_add_u32_e32 v0, 0x8000, v173
	v_cvt_pk_bf16_f32 v34, v34, v35
	v_cvt_pk_bf16_f32 v35, v36, v37
	v_cvt_pk_bf16_f32 v36, v38, v39
	v_cvt_pk_bf16_f32 v37, v40, v41
	ds_write2_b64 v0, v[50:51], v[52:53] offset0:64 offset1:66
	v_cvt_pk_bf16_f32 v50, v58, v59
	v_cvt_pk_bf16_f32 v51, v60, v61
	v_cvt_pk_bf16_f32 v52, v62, v63
	v_cvt_pk_bf16_f32 v53, v64, v65
	ds_write2_b64 v0, v[34:35], v[36:37] offset0:72 offset1:74
	v_cvt_pk_bf16_f32 v34, v42, v43
	v_cvt_pk_bf16_f32 v35, v44, v45
	v_cvt_pk_bf16_f32 v36, v46, v47
	v_cvt_pk_bf16_f32 v37, v48, v49
	v_cvt_pk_bf16_f32 v114, v114, v115
	v_cvt_pk_bf16_f32 v115, v116, v117
	v_cvt_pk_bf16_f32 v116, v118, v119
	v_cvt_pk_bf16_f32 v117, v120, v121
	v_cvt_pk_bf16_f32 v98, v98, v99
	v_cvt_pk_bf16_f32 v99, v100, v101
	v_cvt_pk_bf16_f32 v100, v102, v103
	v_cvt_pk_bf16_f32 v101, v104, v105
	ds_write2_b64 v0, v[50:51], v[52:53] offset0:68 offset1:70
	ds_write2_b64 v0, v[34:35], v[36:37] offset0:76 offset1:78
	v_cvt_pk_bf16_f32 v18, v18, v19
	v_cvt_pk_bf16_f32 v19, v20, v21
	v_cvt_pk_bf16_f32 v20, v22, v23
	v_cvt_pk_bf16_f32 v21, v24, v25
	v_add_u32_e32 v0, 0xc000, v173
	v_cvt_pk_bf16_f32 v2, v2, v3
	v_cvt_pk_bf16_f32 v3, v4, v5
	v_cvt_pk_bf16_f32 v4, v6, v7
	v_cvt_pk_bf16_f32 v5, v8, v9
	ds_write2_b64 v173, v[114:115], v[116:117] offset1:2
	v_cvt_pk_bf16_f32 v114, v122, v123
	v_cvt_pk_bf16_f32 v115, v124, v125
	v_cvt_pk_bf16_f32 v116, v126, v127
	v_cvt_pk_bf16_f32 v117, v128, v129
	ds_write2_b64 v173, v[98:99], v[100:101] offset0:8 offset1:10
	v_cvt_pk_bf16_f32 v98, v106, v107
	v_cvt_pk_bf16_f32 v99, v108, v109
	v_cvt_pk_bf16_f32 v100, v110, v111
	v_cvt_pk_bf16_f32 v101, v112, v113
	ds_write2_b64 v0, v[18:19], v[20:21] offset0:96 offset1:98
	v_cvt_pk_bf16_f32 v18, v26, v27
	v_cvt_pk_bf16_f32 v19, v28, v29
	v_cvt_pk_bf16_f32 v20, v30, v31
	v_cvt_pk_bf16_f32 v21, v32, v33
	ds_write2_b64 v0, v[2:3], v[4:5] offset0:104 offset1:106
	v_cvt_pk_bf16_f32 v2, v10, v11
	v_cvt_pk_bf16_f32 v3, v12, v13
	v_cvt_pk_bf16_f32 v4, v14, v15
	v_cvt_pk_bf16_f32 v5, v16, v17
	ds_write2_b64 v173, v[114:115], v[116:117] offset0:4 offset1:6
	ds_write2_b64 v173, v[98:99], v[100:101] offset0:12 offset1:14
	ds_write2_b64 v0, v[18:19], v[20:21] offset0:100 offset1:102
	ds_write2_b64 v0, v[2:3], v[4:5] offset0:108 offset1:110
	s_waitcnt lgkmcnt(0)
	s_barrier
	s_and_saveexec_b64 s[12:13], vcc
	s_mov_b64 s[36:37], 0x27c0080
	s_cbranch_execz .LBB0_165
	v_lshl_or_b32 v42, s28, 7, v157
	v_ashrrev_i32_e32 v43, 31, v42
	v_readlane_b32 s10, v253, 49
	v_lshlrev_b64 v[2:3], 2, v[42:43]
	v_readlane_b32 s11, v253, 50
	v_readlane_b32 s36, v254, 11
	v_readlane_b32 s37, v254, 12
	v_lshl_add_u64 v[6:7], s[10:11], 0, v[2:3]
	v_readlane_b32 s10, v253, 51
	v_readlane_b32 s11, v253, 52
	v_readlane_b32 s38, v254, 13
	v_readlane_b32 s39, v254, 14
	v_lshl_add_u64 v[10:11], s[10:11], 0, v[2:3]
	v_readlane_b32 s10, v253, 53
	v_readlane_b32 s11, v253, 54
	v_lshl_add_u64 v[4:5], s[36:37], 0, v[2:3]
	v_lshl_add_u64 v[26:27], s[38:39], 0, v[2:3]
	v_lshl_add_u64 v[14:15], s[10:11], 0, v[2:3]
	v_readlane_b32 s10, v253, 55
	v_readlane_b32 s11, v253, 56
	v_lshlrev_b64 v[46:47], 1, v[42:43]
	v_mov_b32_e32 v0, v169
	v_lshl_add_u64 v[18:19], s[10:11], 0, v[2:3]
	v_readlane_b32 s10, v253, 57
	v_readlane_b32 s11, v253, 58
	v_readlane_b32 s40, v254, 15
	v_readlane_b32 s41, v254, 16
	v_lshl_add_u64 v[22:23], s[10:11], 0, v[2:3]
	v_readlane_b32 s10, v253, 59
	v_readlane_b32 s11, v253, 60
	v_readlane_b32 s42, v254, 17
	v_readlane_b32 s43, v254, 18
	v_lshl_add_u64 v[30:31], s[10:11], 0, v[2:3]
	global_load_dwordx4 v[2:5], v[4:5], off
	s_nop 0
	global_load_dwordx4 v[6:9], v[6:7], off
	s_nop 0
	global_load_dwordx4 v[10:13], v[10:11], off
	s_nop 0
	global_load_dwordx4 v[14:17], v[14:15], off
	s_nop 0
	global_load_dwordx4 v[18:21], v[18:19], off
	s_nop 0
	global_load_dwordx4 v[22:25], v[22:23], off
	s_nop 0
	global_load_dwordx4 v[26:29], v[26:27], off
	s_nop 0
	global_load_dwordx4 v[30:33], v[30:31], off
	ds_read2_b64 v[36:39], v174 offset0:65 offset1:97
	ds_read2_b64 v[58:61], v174 offset1:32
	s_waitcnt lgkmcnt(1)
	v_and_b32_e32 v35, 0xffff0000, v37
	v_lshlrev_b32_e32 v34, 16, v37
	v_and_b32_e32 v41, 0xffff0000, v36
	v_lshlrev_b32_e32 v40, 16, v36
	v_lshlrev_b32_e32 v36, 16, v39
	v_and_b32_e32 v37, 0xffff0000, v39
	s_waitcnt lgkmcnt(0)
	v_lshlrev_b32_e32 v48, 16, v61
	v_and_b32_e32 v49, 0xffff0000, v61
	v_lshlrev_b32_e32 v52, 16, v59
	v_and_b32_e32 v53, 0xffff0000, v59
	v_lshlrev_b32_e32 v44, 16, v38
	v_and_b32_e32 v45, 0xffff0000, v38
	v_lshlrev_b32_e32 v54, 16, v60
	v_and_b32_e32 v55, 0xffff0000, v60
	v_lshlrev_b32_e32 v56, 16, v58
	v_and_b32_e32 v57, 0xffff0000, v58
	s_and_saveexec_b64 s[14:15], s[6:7]
	s_cbranch_execz .LBB0_179
	s_add_i32 s10, s27, -2
	v_mad_i64_i32 v[38:39], s[10:11], s10, v216, v[46:47]
	v_lshl_add_u64 v[38:39], v[154:155], 0, v[38:39]
	s_mov_b64 s[16:17], 0
	v_mov_b32_e32 v0, v171
	v_mov_b32_e32 v62, v172
	v_mov_b32_e32 v64, v168
	s_mov_b64 s[22:23], 0x1600
	s_waitcnt vmcnt(0)
	s_branch .LBB0_176
